# gMLP gelu(u) loads widened from 2x16 8-byte to 2x8 16-byte per lane (v_permlane32_swap redistributes the pieces), on top of the store widenings
# speedup vs baseline: 1.0173x; 1.0042x over previous
; __device__ __forceinline__ void gmlp_unit(const GmlpP& P, int b, int ch, LAS unsigned char* lds, int wave, int lane_in) {
;     ...
; #pragma unroll
;         for (int hf = 0; hf < 2; ++hf) {
;             float yv[8][8];
; #pragma unroll
;             for (int i = 0; i < 8; ++i) {
;                 const u32x4 raw = rawv[8 * hf + i];
;                 float v[8];
; #pragma unroll
;                 for (int j = 0; j < 4; ++j) { v[2 * j] = __builtin_bit_cast(float, raw[j] << 16); v[2 * j + 1] = __builtin_bit_cast(float, raw[j] & 0xffff0000u); }
;                 float sm = 0.f;
; #pragma unroll
;                 for (int j = 0; j < 8; ++j) sm += v[j];
;                 sm = row16_sum(sm);
;                 const float mu = sm * (1.0f / 128.0f);
;                 float sq = 0.f;
; #pragma unroll
;                 for (int j = 0; j < 8; ++j) { v[j] -= mu; sq += v[j] * v[j]; }
;                 sq = row16_sum(sq);
;                 const float rs = __builtin_amdgcn_rsqf(sq * (1.0f / 128.0f) + EPS);
; #pragma unroll
;                 for (int j = 0; j < 8; ++j) yv[j][i] = v[j] * rs * (j < 4 ? ga0[j & 3] : ga1[j & 3]) + (j < 4 ? be0[j & 3] : be1[j & 3]);
;             }
.LBB0_541:
	s_or_b64 exec, exec, s[26:27]
	v_add_u32_e32 v109, s20, v86
	s_waitcnt vmcnt(14)
	v_lshlrev_b32_e32 v87, 16, v78
	v_lshlrev_b32_e32 v86, 16, v74
	s_waitcnt vmcnt(0)
	v_and_b32_e32 v82, 0xffff0000, v77
	v_lshlrev_b32_e32 v85, 16, v81
	v_lshlrev_b32_e32 v84, 16, v77
	v_and_b32_e32 v83, 0xffff0000, v81
	v_and_b32_e32 v89, 0xffff0000, v78
	v_and_b32_e32 v88, 0xffff0000, v74
	v_lshlrev_b32_e32 v90, 16, v75
	v_and_b32_e32 v78, 0xffff0000, v75
	v_lshlrev_b32_e32 v75, 16, v80
	v_and_b32_e32 v77, 0xffff0000, v80
	v_pk_add_f32 v[80:81], v[86:87], 0 op_sel_hi:[1,0]
	v_lshlrev_b32_e32 v91, 16, v79
	v_pk_add_f32 v[80:81], v[80:81], v[88:89]
	v_and_b32_e32 v79, 0xffff0000, v79
	v_pk_add_f32 v[80:81], v[80:81], v[90:91]
	v_lshlrev_b32_e32 v74, 16, v76
	v_pk_add_f32 v[80:81], v[80:81], v[78:79]
	v_and_b32_e32 v76, 0xffff0000, v76
	v_pk_add_f32 v[80:81], v[80:81], v[74:75]
	v_mov_b32_e32 v98, v82
	v_pk_add_f32 v[80:81], v[80:81], v[76:77]
	v_mov_b32_e32 v99, v84
	v_pk_add_f32 v[80:81], v[80:81], v[84:85]
	v_mov_b32_e32 v84, v83
	v_pk_add_f32 v[80:81], v[80:81], v[82:83]
	v_mov_b32_e32 v94, v76
	v_mov_b32_e32 v95, v74
	v_mov_b32_dpp v92, v80 row_ror:8 row_mask:0xf bank_mask:0xf bound_ctrl:1
	v_mov_b32_dpp v93, v81 row_ror:8 row_mask:0xf bank_mask:0xf bound_ctrl:1
	v_pk_add_f32 v[80:81], v[80:81], v[92:93]
	v_mov_b32_e32 v74, v77
	v_lshlrev_b32_e32 v106, 3, v108
	v_mov_b32_dpp v92, v80 row_ror:4 row_mask:0xf bank_mask:0xf bound_ctrl:1
	v_mov_b32_dpp v93, v81 row_ror:4 row_mask:0xf bank_mask:0xf bound_ctrl:1
	v_pk_add_f32 v[80:81], v[80:81], v[92:93]
	v_lshlrev_b32_e32 v107, 16, v71
	v_and_b32_e32 v71, 0xffff0000, v71
	v_mov_b32_dpp v92, v80 quad_perm:[2,3,0,1] row_mask:0xf bank_mask:0xf bound_ctrl:1
	v_mov_b32_dpp v93, v81 quad_perm:[2,3,0,1] row_mask:0xf bank_mask:0xf bound_ctrl:1
	v_pk_add_f32 v[80:81], v[80:81], v[92:93]
	v_lshlrev_b32_e32 v124, 16, v63
	v_lshlrev_b32_e32 v125, 16, v59
	v_mov_b32_dpp v92, v80 quad_perm:[1,0,3,2] row_mask:0xf bank_mask:0xf bound_ctrl:1
	v_mov_b32_dpp v93, v81 quad_perm:[1,0,3,2] row_mask:0xf bank_mask:0xf bound_ctrl:1
	v_pk_add_f32 v[80:81], v[80:81], v[92:93]
	v_and_b32_e32 v59, 0xffff0000, v59
	v_pk_mul_f32 v[92:93], v[80:81], s[24:25] op_sel_hi:[1,0]
	v_pk_fma_f32 v[82:83], v[80:81], s[24:25], v[88:89] op_sel_hi:[1,0,1] neg_lo:[1,0,0] neg_hi:[1,0,0]
	v_pk_fma_f32 v[86:87], v[80:81], s[24:25], v[86:87] op_sel_hi:[1,0,1] neg_lo:[1,0,0] neg_hi:[1,0,0]
	v_pk_add_f32 v[104:105], v[84:85], v[92:93] op_sel:[0,1] neg_lo:[0,1] neg_hi:[0,1]
	v_pk_mul_f32 v[84:85], v[82:83], v[82:83]
	v_pk_fma_f32 v[88:89], v[80:81], s[24:25], v[90:91] op_sel_hi:[1,0,1] neg_lo:[1,0,0] neg_hi:[1,0,0]
	v_pk_fma_f32 v[84:85], v[86:87], v[86:87], v[84:85]
	v_pk_add_f32 v[96:97], v[94:95], v[92:93] op_sel_hi:[1,0] neg_lo:[0,1] neg_hi:[0,1]
	v_pk_add_f32 v[102:103], v[74:75], v[92:93] op_sel:[0,1] neg_lo:[0,1] neg_hi:[0,1]
	v_pk_fma_f32 v[84:85], v[88:89], v[88:89], v[84:85]
	v_pk_fma_f32 v[78:79], v[80:81], s[24:25], v[78:79] op_sel_hi:[1,0,1] neg_lo:[1,0,0] neg_hi:[1,0,0]
	v_pk_mul_f32 v[94:95], v[96:97], v[96:97]
	v_pk_mul_f32 v[74:75], v[102:103], v[102:103]
	v_pk_fma_f32 v[80:81], v[78:79], v[78:79], v[84:85]
	v_pk_add_f32 v[98:99], v[98:99], v[92:93] op_sel_hi:[1,0] neg_lo:[0,1] neg_hi:[0,1]
	v_add_f32_e32 v80, v95, v80
	v_add_f32_e32 v75, v75, v81
	v_pk_mul_f32 v[100:101], v[98:99], v[98:99]
	v_pk_mul_f32 v[76:77], v[104:105], v[104:105]
	v_add_f32_e32 v80, v94, v80
	v_add_f32_e32 v74, v74, v75
	v_add_f32_e32 v80, v101, v80
	v_add_f32_e32 v74, v77, v74
	v_add_f32_e32 v80, v100, v80
	v_add_f32_e32 v74, v76, v74
	v_and_b32_e32 v154, 31, v139
	v_add_f32_dpp v80, v80, v80 row_ror:8 row_mask:0xf bank_mask:0xf bound_ctrl:1
	v_add_f32_dpp v74, v74, v74 row_ror:8 row_mask:0xf bank_mask:0xf bound_ctrl:1
	v_ashrrev_i32_e32 v140, 5, v139
	v_add_f32_dpp v80, v80, v80 row_ror:4 row_mask:0xf bank_mask:0xf bound_ctrl:1
	v_add_f32_dpp v74, v74, v74 row_ror:4 row_mask:0xf bank_mask:0xf bound_ctrl:1
	v_bfe_u32 v188, v139, 3, 2
	v_add_f32_dpp v80, v80, v80 quad_perm:[2,3,0,1] row_mask:0xf bank_mask:0xf bound_ctrl:1
	v_add_f32_dpp v74, v74, v74 quad_perm:[2,3,0,1] row_mask:0xf bank_mask:0xf bound_ctrl:1
	v_add_u32_e32 v152, 2, v140
	v_add_f32_dpp v80, v80, v80 quad_perm:[1,0,3,2] row_mask:0xf bank_mask:0xf bound_ctrl:1
	v_add_f32_dpp v74, v74, v74 quad_perm:[1,0,3,2] row_mask:0xf bank_mask:0xf bound_ctrl:1
	v_fmamk_f32 v80, v80, 0x3c000000, v1
	v_fmamk_f32 v74, v74, 0x3c000000, v1
	v_rsq_f32_e32 v100, v80
	v_rsq_f32_e32 v101, v74
	v_or_b32_e32 v74, s6, v106
	v_mul_lo_u32 v74, v74, s48
	v_add_u32_e32 v75, 0, v74
	v_pk_mul_f32 v[76:77], v[86:87], v[100:101]
	v_pk_mul_f32 v[78:79], v[78:79], v[100:101]
	v_pk_fma_f32 v[94:95], v[10:11], v[76:77], v[14:15] op_sel_hi:[0,1,0]
	v_pk_mul_f32 v[76:77], v[82:83], v[100:101]
	v_mov_b32_e32 v74, v13
	v_pk_fma_f32 v[92:93], v[10:11], v[76:77], v[14:15] op_sel:[1,0,1]
	v_pk_mul_f32 v[76:77], v[88:89], v[100:101]
	v_mov_b32_e32 v80, v7
	v_pk_fma_f32 v[90:91], v[12:13], v[76:77], v[16:17] op_sel_hi:[0,1,0]
	v_mov_b32_e32 v76, v17
	v_pk_fma_f32 v[88:89], v[74:75], v[78:79], v[76:77] op_sel_hi:[0,1,0]
	v_mov_b32_e32 v78, v97
	v_mov_b32_e32 v79, v103
	v_pk_mul_f32 v[78:79], v[78:79], v[100:101]
	v_mov_b32_e32 v97, v102
	v_pk_fma_f32 v[86:87], v[2:3], v[78:79], v[6:7] op_sel_hi:[0,1,0]
	v_pk_mul_f32 v[82:83], v[96:97], v[100:101]
	v_mov_b32_e32 v78, v3
	v_pk_fma_f32 v[84:85], v[78:79], v[82:83], v[80:81] op_sel_hi:[0,1,0]
	v_mov_b32_e32 v82, v99
	v_mov_b32_e32 v83, v105
	v_mov_b32_e32 v99, v104
	v_lshlrev_b32_e32 v103, 16, v70
	v_lshlrev_b32_e32 v102, 16, v66
	v_pk_mul_f32 v[82:83], v[82:83], v[100:101]
; __device__ __forceinline__ void gmlp_unit(const GmlpP& P, int b, int ch, LAS unsigned char* lds, int wave, int lane_in) {
;     ...
;             for (int i = 0; i < 8; ++i) {
;                 const u32x4 raw = rawv[8 * hf + i];
;                 float v[8];
; #pragma unroll
;                 for (int j = 0; j < 4; ++j) { v[2 * j] = __builtin_bit_cast(float, raw[j] << 16); v[2 * j + 1] = __builtin_bit_cast(float, raw[j] & 0xffff0000u); }
;                 float sm = 0.f;
; #pragma unroll
;                 for (int j = 0; j < 8; ++j) sm += v[j];
;                 sm = row16_sum(sm);
;                 const float mu = sm * (1.0f / 128.0f);
;                 float sq = 0.f;
; #pragma unroll
;                 for (int j = 0; j < 8; ++j) { v[j] -= mu; sq += v[j] * v[j]; }
;                 sq = row16_sum(sq);
;                 const float rs = __builtin_amdgcn_rsqf(sq * (1.0f / 128.0f) + EPS);
; #pragma unroll
;                 for (int j = 0; j < 8; ++j) yv[j][i] = v[j] * rs * (j < 4 ? ga0[j & 3] : ga1[j & 3]) + (j < 4 ? be0[j & 3] : be1[j & 3]);
;             }
	v_pk_mul_f32 v[96:97], v[98:99], v[100:101]
	v_and_b32_e32 v98, 0xffff0000, v69
	v_lshlrev_b32_e32 v101, 16, v73
	v_lshlrev_b32_e32 v100, 16, v69
	v_and_b32_e32 v99, 0xffff0000, v73
	v_and_b32_e32 v105, 0xffff0000, v70
	v_and_b32_e32 v104, 0xffff0000, v66
	v_lshlrev_b32_e32 v106, 16, v67
	v_and_b32_e32 v70, 0xffff0000, v67
	v_lshlrev_b32_e32 v67, 16, v72
	v_and_b32_e32 v69, 0xffff0000, v72
	v_pk_add_f32 v[72:73], v[102:103], 0 op_sel_hi:[1,0]
	v_lshlrev_b32_e32 v66, 16, v68
	v_pk_add_f32 v[72:73], v[72:73], v[104:105]
	v_and_b32_e32 v68, 0xffff0000, v68
	v_pk_add_f32 v[72:73], v[72:73], v[106:107]
	v_mov_b32_e32 v112, v68
	v_pk_add_f32 v[72:73], v[72:73], v[70:71]
	v_mov_b32_e32 v113, v66
	v_pk_add_f32 v[72:73], v[72:73], v[66:67]
	v_mov_b32_e32 v116, v98
	v_pk_add_f32 v[72:73], v[72:73], v[68:69]
	v_mov_b32_e32 v117, v100
	v_pk_add_f32 v[72:73], v[72:73], v[100:101]
	v_mov_b32_e32 v66, v69
	v_pk_add_f32 v[72:73], v[72:73], v[98:99]
	v_mov_b32_e32 v100, v99
	v_pk_fma_f32 v[82:83], v[4:5], v[82:83], v[8:9] op_sel_hi:[0,1,0]
	v_mov_b32_dpp v110, v72 row_ror:8 row_mask:0xf bank_mask:0xf bound_ctrl:1
	v_mov_b32_dpp v111, v73 row_ror:8 row_mask:0xf bank_mask:0xf bound_ctrl:1
	v_pk_add_f32 v[72:73], v[72:73], v[110:111]
	v_xor_b32_e32 v153, v188, v152
	v_cmp_gt_u32_e32 vcc, 32, v139
	v_mov_b32_dpp v110, v72 row_ror:4 row_mask:0xf bank_mask:0xf bound_ctrl:1
	v_mov_b32_dpp v111, v73 row_ror:4 row_mask:0xf bank_mask:0xf bound_ctrl:1
	v_pk_add_f32 v[72:73], v[72:73], v[110:111]
	s_nop 1
	v_mov_b32_dpp v110, v72 quad_perm:[2,3,0,1] row_mask:0xf bank_mask:0xf bound_ctrl:1
	v_mov_b32_dpp v111, v73 quad_perm:[2,3,0,1] row_mask:0xf bank_mask:0xf bound_ctrl:1
	v_pk_add_f32 v[72:73], v[72:73], v[110:111]
	s_nop 1
	v_mov_b32_dpp v110, v72 quad_perm:[1,0,3,2] row_mask:0xf bank_mask:0xf bound_ctrl:1
	v_mov_b32_dpp v111, v73 quad_perm:[1,0,3,2] row_mask:0xf bank_mask:0xf bound_ctrl:1
	v_pk_add_f32 v[72:73], v[72:73], v[110:111]
	s_nop 0
	v_pk_mul_f32 v[110:111], v[72:73], s[24:25] op_sel_hi:[1,0]
	v_pk_fma_f32 v[98:99], v[72:73], s[24:25], v[104:105] op_sel_hi:[1,0,1] neg_lo:[1,0,0] neg_hi:[1,0,0]
	v_pk_fma_f32 v[102:103], v[72:73], s[24:25], v[102:103] op_sel_hi:[1,0,1] neg_lo:[1,0,0] neg_hi:[1,0,0]
	v_pk_add_f32 v[112:113], v[112:113], v[110:111] op_sel_hi:[1,0] neg_lo:[0,1] neg_hi:[0,1]
	v_pk_add_f32 v[116:117], v[116:117], v[110:111] op_sel_hi:[1,0] neg_lo:[0,1] neg_hi:[0,1]
	v_pk_add_f32 v[120:121], v[66:67], v[110:111] op_sel:[0,1] neg_lo:[0,1] neg_hi:[0,1]
	v_pk_add_f32 v[110:111], v[100:101], v[110:111] op_sel:[0,1] neg_lo:[0,1] neg_hi:[0,1]
	v_pk_mul_f32 v[100:101], v[98:99], v[98:99]
	v_pk_fma_f32 v[122:123], v[72:73], s[24:25], v[106:107] op_sel_hi:[1,0,1] neg_lo:[1,0,0] neg_hi:[1,0,0]
	v_pk_fma_f32 v[100:101], v[102:103], v[102:103], v[100:101]
	v_pk_fma_f32 v[72:73], v[72:73], s[24:25], v[70:71] op_sel_hi:[1,0,1] neg_lo:[1,0,0] neg_hi:[1,0,0]
	v_pk_fma_f32 v[100:101], v[122:123], v[122:123], v[100:101]
	v_pk_mul_f32 v[114:115], v[112:113], v[112:113]
	v_pk_fma_f32 v[70:71], v[72:73], v[72:73], v[100:101]
	v_pk_mul_f32 v[118:119], v[116:117], v[116:117]
	v_add_f32_e32 v3, v115, v70
	v_add_f32_e32 v3, v114, v3
	v_add_f32_e32 v3, v119, v3
	v_add_f32_e32 v3, v118, v3
	v_pk_mul_f32 v[66:67], v[120:121], v[120:121]
	v_pk_mul_f32 v[68:69], v[110:111], v[110:111]
	v_add_f32_dpp v3, v3, v3 row_ror:8 row_mask:0xf bank_mask:0xf bound_ctrl:1
	v_lshlrev_b32_e32 v119, 16, v61
	v_lshlrev_b32_e32 v118, 16, v65
	v_add_f32_dpp v3, v3, v3 row_ror:4 row_mask:0xf bank_mask:0xf bound_ctrl:1
	v_mov_b32_e32 v133, v118
	s_nop 0
	v_add_f32_dpp v3, v3, v3 quad_perm:[2,3,0,1] row_mask:0xf bank_mask:0xf bound_ctrl:1
	s_nop 1
	v_add_f32_dpp v3, v3, v3 quad_perm:[1,0,3,2] row_mask:0xf bank_mask:0xf bound_ctrl:1
	v_fmamk_f32 v3, v3, 0x3c000000, v1
	v_rsq_f32_e32 v114, v3
	v_add_f32_e32 v3, v67, v71
	v_add_f32_e32 v3, v66, v3
	v_add_f32_e32 v3, v69, v3
	v_add_f32_e32 v3, v68, v3
	v_mov_b32_e32 v66, v5
	v_mov_b32_e32 v68, v9
	v_add_f32_dpp v3, v3, v3 row_ror:8 row_mask:0xf bank_mask:0xf bound_ctrl:1
	v_pk_fma_f32 v[70:71], v[66:67], v[96:97], v[68:69] op_sel_hi:[0,1,0]
	s_nop 0
	v_add_f32_dpp v3, v3, v3 row_ror:4 row_mask:0xf bank_mask:0xf bound_ctrl:1
	s_nop 1
	v_add_f32_dpp v3, v3, v3 quad_perm:[2,3,0,1] row_mask:0xf bank_mask:0xf bound_ctrl:1
	s_nop 1
	v_add_f32_dpp v3, v3, v3 quad_perm:[1,0,3,2] row_mask:0xf bank_mask:0xf bound_ctrl:1
	v_fmamk_f32 v3, v3, 0x3c000000, v1
	v_rsq_f32_e32 v115, v3
	s_nop 0
	v_pk_mul_f32 v[72:73], v[72:73], v[114:115]
	v_pk_mul_f32 v[96:97], v[102:103], v[114:115]
	v_pk_fma_f32 v[100:101], v[74:75], v[72:73], v[76:77] op_sel_hi:[0,1,0]
	v_mov_b32_e32 v72, v113
	v_mov_b32_e32 v73, v121
	v_pk_fma_f32 v[106:107], v[10:11], v[96:97], v[14:15] op_sel_hi:[0,1,0]
	v_pk_mul_f32 v[96:97], v[98:99], v[114:115]
	v_pk_mul_f32 v[72:73], v[72:73], v[114:115]
	v_mov_b32_e32 v113, v120
	v_lshlrev_b32_e32 v121, 16, v58
	v_lshlrev_b32_e32 v120, 16, v62
	v_pk_fma_f32 v[104:105], v[10:11], v[96:97], v[14:15] op_sel:[1,0,1]
	v_pk_mul_f32 v[96:97], v[122:123], v[114:115]
	v_pk_fma_f32 v[98:99], v[2:3], v[72:73], v[6:7] op_sel_hi:[0,1,0]
	v_pk_mul_f32 v[72:73], v[112:113], v[114:115]
	v_and_b32_e32 v112, 0xffff0000, v65
	v_and_b32_e32 v113, 0xffff0000, v61
	v_and_b32_e32 v123, 0xffff0000, v58
	v_and_b32_e32 v122, 0xffff0000, v62
	v_and_b32_e32 v58, 0xffff0000, v63
	v_lshlrev_b32_e32 v63, 16, v60
	v_lshlrev_b32_e32 v62, 16, v64
	v_and_b32_e32 v61, 0xffff0000, v60
	v_and_b32_e32 v60, 0xffff0000, v64
	v_pk_add_f32 v[64:65], v[120:121], 0 op_sel_hi:[1,0]
	v_mov_b32_e32 v128, v60
	v_pk_add_f32 v[64:65], v[64:65], v[122:123]
	v_mov_b32_e32 v129, v62
; __device__ __forceinline__ void gmlp_unit(const GmlpP& P, int b, int ch, LAS unsigned char* lds, int wave, int lane_in) {
;     ...
;             for (int i = 0; i < 8; ++i) {
;                 const u32x4 raw = rawv[8 * hf + i];
;                 float v[8];
; #pragma unroll
;                 for (int j = 0; j < 4; ++j) { v[2 * j] = __builtin_bit_cast(float, raw[j] << 16); v[2 * j + 1] = __builtin_bit_cast(float, raw[j] & 0xffff0000u); }
;                 float sm = 0.f;
; #pragma unroll
;                 for (int j = 0; j < 8; ++j) sm += v[j];
;                 sm = row16_sum(sm);
;                 const float mu = sm * (1.0f / 128.0f);
;                 float sq = 0.f;
; #pragma unroll
;                 for (int j = 0; j < 8; ++j) { v[j] -= mu; sq += v[j] * v[j]; }
;                 sq = row16_sum(sq);
;                 const float rs = __builtin_amdgcn_rsqf(sq * (1.0f / 128.0f) + EPS);
; #pragma unroll
;                 for (int j = 0; j < 8; ++j) yv[j][i] = v[j] * rs * (j < 4 ? ga0[j & 3] : ga1[j & 3]) + (j < 4 ? be0[j & 3] : be1[j & 3]);
;             }
	v_pk_add_f32 v[64:65], v[64:65], v[124:125]
	v_mov_b32_e32 v132, v112
	v_pk_add_f32 v[64:65], v[64:65], v[58:59]
	v_pk_fma_f32 v[102:103], v[12:13], v[96:97], v[16:17] op_sel_hi:[0,1,0]
	v_pk_add_f32 v[64:65], v[64:65], v[62:63]
	v_mov_b32_e32 v62, v61
	v_pk_add_f32 v[64:65], v[64:65], v[60:61]
	v_pk_fma_f32 v[96:97], v[78:79], v[72:73], v[80:81] op_sel_hi:[0,1,0]
	v_pk_add_f32 v[64:65], v[64:65], v[118:119]
	v_mov_b32_e32 v118, v113
	v_pk_add_f32 v[64:65], v[64:65], v[112:113]
	v_mov_b32_e32 v72, v117
	v_mov_b32_e32 v73, v111
	v_mov_b32_dpp v126, v64 row_ror:8 row_mask:0xf bank_mask:0xf bound_ctrl:1
	v_mov_b32_dpp v127, v65 row_ror:8 row_mask:0xf bank_mask:0xf bound_ctrl:1
	v_pk_add_f32 v[64:65], v[64:65], v[126:127]
	v_mov_b32_e32 v117, v110
	v_pk_mul_f32 v[72:73], v[72:73], v[114:115]
	v_mov_b32_dpp v126, v64 row_ror:4 row_mask:0xf bank_mask:0xf bound_ctrl:1
	v_mov_b32_dpp v127, v65 row_ror:4 row_mask:0xf bank_mask:0xf bound_ctrl:1
	v_pk_add_f32 v[64:65], v[64:65], v[126:127]
	v_pk_fma_f32 v[72:73], v[4:5], v[72:73], v[8:9] op_sel_hi:[0,1,0]
	s_nop 0
	v_mov_b32_dpp v126, v64 quad_perm:[2,3,0,1] row_mask:0xf bank_mask:0xf bound_ctrl:1
	v_mov_b32_dpp v127, v65 quad_perm:[2,3,0,1] row_mask:0xf bank_mask:0xf bound_ctrl:1
	v_pk_add_f32 v[64:65], v[64:65], v[126:127]
	s_nop 1
	v_mov_b32_dpp v126, v64 quad_perm:[1,0,3,2] row_mask:0xf bank_mask:0xf bound_ctrl:1
	v_mov_b32_dpp v127, v65 quad_perm:[1,0,3,2] row_mask:0xf bank_mask:0xf bound_ctrl:1
	v_pk_add_f32 v[64:65], v[64:65], v[126:127]
	s_nop 0
	v_pk_mul_f32 v[126:127], v[64:65], s[24:25] op_sel_hi:[1,0]
	v_pk_fma_f32 v[122:123], v[64:65], s[24:25], v[122:123] op_sel_hi:[1,0,1] neg_lo:[1,0,0] neg_hi:[1,0,0]
	v_pk_fma_f32 v[120:121], v[64:65], s[24:25], v[120:121] op_sel_hi:[1,0,1] neg_lo:[1,0,0] neg_hi:[1,0,0]
	v_pk_add_f32 v[128:129], v[128:129], v[126:127] op_sel_hi:[1,0] neg_lo:[0,1] neg_hi:[0,1]
	v_pk_add_f32 v[132:133], v[132:133], v[126:127] op_sel_hi:[1,0] neg_lo:[0,1] neg_hi:[0,1]
	v_pk_add_f32 v[60:61], v[62:63], v[126:127] op_sel:[0,1] neg_lo:[0,1] neg_hi:[0,1]
	v_pk_add_f32 v[112:113], v[118:119], v[126:127] op_sel:[0,1] neg_lo:[0,1] neg_hi:[0,1]
	v_pk_mul_f32 v[126:127], v[122:123], v[122:123]
	v_pk_fma_f32 v[124:125], v[64:65], s[24:25], v[124:125] op_sel_hi:[1,0,1] neg_lo:[1,0,0] neg_hi:[1,0,0]
	v_pk_fma_f32 v[126:127], v[120:121], v[120:121], v[126:127]
	v_pk_fma_f32 v[58:59], v[64:65], s[24:25], v[58:59] op_sel_hi:[1,0,1] neg_lo:[1,0,0] neg_hi:[1,0,0]
	v_pk_fma_f32 v[126:127], v[124:125], v[124:125], v[126:127]
	v_pk_mul_f32 v[130:131], v[128:129], v[128:129]
	v_pk_fma_f32 v[64:65], v[58:59], v[58:59], v[126:127]
	v_pk_mul_f32 v[134:135], v[132:133], v[132:133]
	v_add_f32_e32 v3, v131, v64
	v_add_f32_e32 v3, v130, v3
	v_add_f32_e32 v3, v135, v3
	v_add_f32_e32 v3, v134, v3
	v_pk_mul_f32 v[62:63], v[60:61], v[60:61]
	v_pk_mul_f32 v[118:119], v[112:113], v[112:113]
	v_add_f32_dpp v3, v3, v3 row_ror:8 row_mask:0xf bank_mask:0xf bound_ctrl:1
	v_lshlrev_b32_e32 v127, 16, v54
	v_lshlrev_b32_e32 v126, 16, v50
	v_add_f32_dpp v3, v3, v3 row_ror:4 row_mask:0xf bank_mask:0xf bound_ctrl:1
	v_lshlrev_b32_e32 v130, 16, v51
	v_lshlrev_b32_e32 v131, 16, v55
	v_add_f32_dpp v3, v3, v3 quad_perm:[2,3,0,1] row_mask:0xf bank_mask:0xf bound_ctrl:1
	v_and_b32_e32 v55, 0xffff0000, v55
	s_nop 0
	v_add_f32_dpp v3, v3, v3 quad_perm:[1,0,3,2] row_mask:0xf bank_mask:0xf bound_ctrl:1
	v_fmamk_f32 v3, v3, 0x3c000000, v1
	v_rsq_f32_e32 v64, v3
	v_add_f32_e32 v3, v63, v65
	v_add_f32_e32 v3, v62, v3
	v_add_f32_e32 v3, v119, v3
	v_add_f32_e32 v3, v118, v3
	v_mov_b32_e32 v118, v129
	v_mov_b32_e32 v129, v60
	v_add_f32_dpp v3, v3, v3 row_ror:8 row_mask:0xf bank_mask:0xf bound_ctrl:1
	v_pk_mul_f32 v[62:63], v[116:117], v[114:115]
	v_mov_b32_e32 v119, v61
	v_add_f32_dpp v3, v3, v3 row_ror:4 row_mask:0xf bank_mask:0xf bound_ctrl:1
	v_pk_fma_f32 v[62:63], v[66:67], v[62:63], v[68:69] op_sel_hi:[0,1,0]
	s_nop 0
	v_add_f32_dpp v3, v3, v3 quad_perm:[2,3,0,1] row_mask:0xf bank_mask:0xf bound_ctrl:1
	s_nop 1
	v_add_f32_dpp v3, v3, v3 quad_perm:[1,0,3,2] row_mask:0xf bank_mask:0xf bound_ctrl:1
	v_fmamk_f32 v3, v3, 0x3c000000, v1
	v_rsq_f32_e32 v65, v3
	s_nop 0
	v_pk_mul_f32 v[114:115], v[122:123], v[64:65]
	v_pk_mul_f32 v[116:117], v[124:125], v[64:65]
	v_pk_mul_f32 v[60:61], v[128:129], v[64:65]
	v_and_b32_e32 v122, 0xffff0000, v53
	v_lshlrev_b32_e32 v125, 16, v57
	v_lshlrev_b32_e32 v124, 16, v53
	v_and_b32_e32 v123, 0xffff0000, v57
	v_and_b32_e32 v129, 0xffff0000, v54
	v_and_b32_e32 v128, 0xffff0000, v50
	v_and_b32_e32 v54, 0xffff0000, v51
	v_lshlrev_b32_e32 v51, 16, v56
	v_and_b32_e32 v53, 0xffff0000, v56
	v_pk_add_f32 v[56:57], v[126:127], 0 op_sel_hi:[1,0]
	v_lshlrev_b32_e32 v50, 16, v52
	v_pk_add_f32 v[56:57], v[56:57], v[128:129]
	v_and_b32_e32 v52, 0xffff0000, v52
	v_pk_add_f32 v[56:57], v[56:57], v[130:131]
	v_mov_b32_e32 v136, v52
	v_pk_add_f32 v[56:57], v[56:57], v[54:55]
	v_mov_b32_e32 v137, v50
	v_pk_add_f32 v[56:57], v[56:57], v[50:51]
	v_mov_b32_e32 v146, v122
	v_pk_add_f32 v[56:57], v[56:57], v[52:53]
	v_mov_b32_e32 v147, v124
	v_pk_add_f32 v[56:57], v[56:57], v[124:125]
	v_mov_b32_e32 v50, v53
	v_pk_add_f32 v[56:57], v[56:57], v[122:123]
	v_mov_b32_e32 v124, v123
	v_pk_mul_f32 v[118:119], v[118:119], v[64:65]
	v_mov_b32_dpp v134, v56 row_ror:8 row_mask:0xf bank_mask:0xf bound_ctrl:1
	v_mov_b32_dpp v135, v57 row_ror:8 row_mask:0xf bank_mask:0xf bound_ctrl:1
	v_pk_add_f32 v[56:57], v[56:57], v[134:135]
	v_pk_fma_f32 v[118:119], v[2:3], v[118:119], v[6:7] op_sel_hi:[0,1,0]
	v_pk_mul_f32 v[110:111], v[120:121], v[64:65]
	v_mov_b32_dpp v134, v56 row_ror:4 row_mask:0xf bank_mask:0xf bound_ctrl:1
; #define LAS __attribute__((address_space(3)))
; __device__ __forceinline__ unsigned pk2(float lo, float hi) { f32x2 v = {lo, hi}; bf16x2_t b = __builtin_convertvector(v, bf16x2_t); return __builtin_bit_cast(unsigned, b); }
; __device__ __forceinline__ void gmlp_unit(const GmlpP& P, int b, int ch, LAS unsigned char* lds, int wave, int lane_in) {
;     ...
;             for (int i = 0; i < 8; ++i) {
;                 const u32x4 raw = rawv[8 * hf + i];
;                 float v[8];
; #pragma unroll
;                 for (int j = 0; j < 4; ++j) { v[2 * j] = __builtin_bit_cast(float, raw[j] << 16); v[2 * j + 1] = __builtin_bit_cast(float, raw[j] & 0xffff0000u); }
;                 float sm = 0.f;
; #pragma unroll
;                 for (int j = 0; j < 8; ++j) sm += v[j];
;                 sm = row16_sum(sm);
;                 const float mu = sm * (1.0f / 128.0f);
;                 float sq = 0.f;
; #pragma unroll
;                 for (int j = 0; j < 8; ++j) { v[j] -= mu; sq += v[j] * v[j]; }
;                 sq = row16_sum(sq);
;                 const float rs = __builtin_amdgcn_rsqf(sq * (1.0f / 128.0f) + EPS);
; #pragma unroll
;                 for (int j = 0; j < 8; ++j) yv[j][i] = v[j] * rs * (j < 4 ? ga0[j & 3] : ga1[j & 3]) + (j < 4 ? be0[j & 3] : be1[j & 3]);
;             }
;             const int s0 = 64 * th + 16 * rr + 8 * hf;
;             LAS unsigned char* dst = lds + (gI * 128 + 8 * sub) * LDS_TT_PITCH + 16 * ((s0 >> 3) ^ sub);
; #pragma unroll
;             for (int j = 0; j < 8; ++j) {
;                 u32x4 w; w.x = pk2(yv[j][0], yv[j][1]); w.y = pk2(yv[j][2], yv[j][3]); w.z = pk2(yv[j][4], yv[j][5]); w.w = pk2(yv[j][6], yv[j][7]);
;                 *(LAS u32x4*)(dst + j * LDS_TT_PITCH) = w;
;             }
	v_mov_b32_dpp v135, v57 row_ror:4 row_mask:0xf bank_mask:0xf bound_ctrl:1
	v_pk_add_f32 v[56:57], v[56:57], v[134:135]
	v_mov_b32_e32 v120, v133
	v_mov_b32_e32 v133, v112
	v_mov_b32_dpp v134, v56 quad_perm:[2,3,0,1] row_mask:0xf bank_mask:0xf bound_ctrl:1
	v_mov_b32_dpp v135, v57 quad_perm:[2,3,0,1] row_mask:0xf bank_mask:0xf bound_ctrl:1
	v_pk_add_f32 v[56:57], v[56:57], v[134:135]
	v_mov_b32_e32 v121, v113
	v_pk_mul_f32 v[58:59], v[58:59], v[64:65]
	v_mov_b32_dpp v134, v56 quad_perm:[1,0,3,2] row_mask:0xf bank_mask:0xf bound_ctrl:1
	v_mov_b32_dpp v135, v57 quad_perm:[1,0,3,2] row_mask:0xf bank_mask:0xf bound_ctrl:1
	v_pk_add_f32 v[56:57], v[56:57], v[134:135]
	v_pk_mul_f32 v[120:121], v[120:121], v[64:65]
	v_pk_mul_f32 v[134:135], v[56:57], s[24:25] op_sel_hi:[1,0]
	v_pk_fma_f32 v[128:129], v[56:57], s[24:25], v[128:129] op_sel_hi:[1,0,1] neg_lo:[1,0,0] neg_hi:[1,0,0]
	v_pk_fma_f32 v[126:127], v[56:57], s[24:25], v[126:127] op_sel_hi:[1,0,1] neg_lo:[1,0,0] neg_hi:[1,0,0]
	v_pk_add_f32 v[136:137], v[136:137], v[134:135] op_sel_hi:[1,0] neg_lo:[0,1] neg_hi:[0,1]
	v_pk_add_f32 v[146:147], v[146:147], v[134:135] op_sel_hi:[1,0] neg_lo:[0,1] neg_hi:[0,1]
	v_pk_add_f32 v[50:51], v[50:51], v[134:135] op_sel:[0,1] neg_lo:[0,1] neg_hi:[0,1]
	v_pk_add_f32 v[122:123], v[124:125], v[134:135] op_sel:[0,1] neg_lo:[0,1] neg_hi:[0,1]
	v_pk_mul_f32 v[134:135], v[128:129], v[128:129]
	v_pk_fma_f32 v[130:131], v[56:57], s[24:25], v[130:131] op_sel_hi:[1,0,1] neg_lo:[1,0,0] neg_hi:[1,0,0]
	v_pk_fma_f32 v[134:135], v[126:127], v[126:127], v[134:135]
	v_pk_fma_f32 v[54:55], v[56:57], s[24:25], v[54:55] op_sel_hi:[1,0,1] neg_lo:[1,0,0] neg_hi:[1,0,0]
	v_pk_fma_f32 v[134:135], v[130:131], v[130:131], v[134:135]
	v_pk_mul_f32 v[144:145], v[136:137], v[136:137]
	v_pk_fma_f32 v[56:57], v[54:55], v[54:55], v[134:135]
	v_pk_mul_f32 v[148:149], v[146:147], v[146:147]
	v_add_f32_e32 v3, v145, v56
	v_add_f32_e32 v3, v144, v3
	v_add_f32_e32 v3, v149, v3
	v_add_f32_e32 v3, v148, v3
	v_pk_mul_f32 v[52:53], v[50:51], v[50:51]
	v_pk_mul_f32 v[124:125], v[122:123], v[122:123]
	v_add_f32_dpp v3, v3, v3 row_ror:8 row_mask:0xf bank_mask:0xf bound_ctrl:1
	v_pk_fma_f32 v[110:111], v[10:11], v[110:111], v[14:15] op_sel_hi:[0,1,0]
	v_pk_fma_f32 v[120:121], v[4:5], v[120:121], v[8:9] op_sel_hi:[0,1,0]
	v_add_f32_dpp v3, v3, v3 row_ror:4 row_mask:0xf bank_mask:0xf bound_ctrl:1
	v_pk_fma_f32 v[114:115], v[10:11], v[114:115], v[14:15] op_sel:[1,0,1]
	v_pk_fma_f32 v[116:117], v[12:13], v[116:117], v[16:17] op_sel_hi:[0,1,0]
	v_add_f32_dpp v3, v3, v3 quad_perm:[2,3,0,1] row_mask:0xf bank_mask:0xf bound_ctrl:1
	v_pk_fma_f32 v[58:59], v[74:75], v[58:59], v[76:77] op_sel_hi:[0,1,0]
	v_pk_fma_f32 v[60:61], v[78:79], v[60:61], v[80:81] op_sel_hi:[0,1,0]
	v_add_f32_dpp v3, v3, v3 quad_perm:[1,0,3,2] row_mask:0xf bank_mask:0xf bound_ctrl:1
	v_fmamk_f32 v3, v3, 0x3c000000, v1
	v_rsq_f32_e32 v56, v3
	v_add_f32_e32 v3, v53, v57
	v_add_f32_e32 v3, v52, v3
	v_add_f32_e32 v3, v125, v3
	v_add_f32_e32 v3, v124, v3
	v_pk_mul_f32 v[52:53], v[132:133], v[64:65]
	s_nop 0
	v_add_f32_dpp v3, v3, v3 row_ror:8 row_mask:0xf bank_mask:0xf bound_ctrl:1
	v_pk_fma_f32 v[64:65], v[66:67], v[52:53], v[68:69] op_sel_hi:[0,1,0]
	s_nop 0
	v_add_f32_dpp v3, v3, v3 row_ror:4 row_mask:0xf bank_mask:0xf bound_ctrl:1
	s_nop 1
	v_add_f32_dpp v3, v3, v3 quad_perm:[2,3,0,1] row_mask:0xf bank_mask:0xf bound_ctrl:1
	s_nop 1
	v_add_f32_dpp v3, v3, v3 quad_perm:[1,0,3,2] row_mask:0xf bank_mask:0xf bound_ctrl:1
	v_fmamk_f32 v3, v3, 0x3c000000, v1
	v_rsq_f32_e32 v57, v3
	s_nop 0
	v_pk_mul_f32 v[52:53], v[126:127], v[56:57]
	s_nop 0
	v_pk_fma_f32 v[112:113], v[10:11], v[52:53], v[14:15] op_sel_hi:[0,1,0]
	v_pk_mul_f32 v[52:53], v[128:129], v[56:57]
	s_nop 0
	v_pk_fma_f32 v[124:125], v[10:11], v[52:53], v[14:15] op_sel:[1,0,1]
	v_pk_mul_f32 v[52:53], v[130:131], v[56:57]
	s_nop 0
	v_pk_fma_f32 v[126:127], v[12:13], v[52:53], v[16:17] op_sel_hi:[0,1,0]
	v_pk_mul_f32 v[52:53], v[54:55], v[56:57]
	s_nop 0
	v_pk_fma_f32 v[54:55], v[74:75], v[52:53], v[76:77] op_sel_hi:[0,1,0]
	v_mov_b32_e32 v52, v137
	v_mov_b32_e32 v137, v50
	v_mov_b32_e32 v53, v51
	v_pk_mul_f32 v[50:51], v[136:137], v[56:57]
	v_pk_mul_f32 v[52:53], v[52:53], v[56:57]
	v_pk_fma_f32 v[130:131], v[78:79], v[50:51], v[80:81] op_sel_hi:[0,1,0]
	v_mov_b32_e32 v50, v147
	v_mov_b32_e32 v51, v123
	v_pk_fma_f32 v[128:129], v[2:3], v[52:53], v[6:7] op_sel_hi:[0,1,0]
	v_pk_mul_f32 v[50:51], v[50:51], v[56:57]
	v_mov_b32_e32 v147, v122
	v_ashrrev_i32_e32 v3, 3, v109
	v_pk_fma_f32 v[132:133], v[4:5], v[50:51], v[8:9] op_sel_hi:[0,1,0]
	v_pk_mul_f32 v[50:51], v[146:147], v[56:57]
	v_xor_b32_e32 v5, v3, v108
	v_pk_fma_f32 v[56:57], v[66:67], v[50:51], v[68:69] op_sel_hi:[0,1,0]
	v_lshl_add_u32 v5, v5, 4, v75
	v_cvt_pk_bf16_f32 v50, v94, v95
	v_cvt_pk_bf16_f32 v51, v106, v107
	v_cvt_pk_bf16_f32 v52, v110, v111
	v_cvt_pk_bf16_f32 v53, v112, v113
	ds_write_b128 v5, v[50:53]
	v_cvt_pk_bf16_f32 v50, v92, v93
	v_cvt_pk_bf16_f32 v51, v104, v105
	v_cvt_pk_bf16_f32 v52, v114, v115
	v_cvt_pk_bf16_f32 v53, v124, v125
	ds_write_b128 v5, v[50:53] offset:272
	v_cvt_pk_bf16_f32 v50, v90, v91
	v_cvt_pk_bf16_f32 v51, v102, v103
	v_cvt_pk_bf16_f32 v52, v116, v117
	v_cvt_pk_bf16_f32 v53, v126, v127
	ds_write_b128 v5, v[50:53] offset:544
	v_cvt_pk_bf16_f32 v50, v88, v89
	v_cvt_pk_bf16_f32 v51, v100, v101
	v_cvt_pk_bf16_f32 v52, v58, v59
	v_cvt_pk_bf16_f32 v53, v54, v55
	ds_write_b128 v5, v[50:53] offset:816
	v_cvt_pk_bf16_f32 v50, v86, v87
	v_cvt_pk_bf16_f32 v51, v98, v99
	v_cvt_pk_bf16_f32 v52, v118, v119
	v_cvt_pk_bf16_f32 v53, v128, v129
	ds_write_b128 v5, v[50:53] offset:1088
	v_cvt_pk_bf16_f32 v50, v84, v85
; #define LAS __attribute__((address_space(3)))
; __device__ __forceinline__ unsigned pk2(float lo, float hi) { f32x2 v = {lo, hi}; bf16x2_t b = __builtin_convertvector(v, bf16x2_t); return __builtin_bit_cast(unsigned, b); }
; __device__ __forceinline__ void gmlp_unit(const GmlpP& P, int b, int ch, LAS unsigned char* lds, int wave, int lane_in) {
;     ...
;             for (int i = 0; i < 8; ++i) {
;                 const u32x4 raw = rawv[8 * hf + i];
;                 float v[8];
; #pragma unroll
;                 for (int j = 0; j < 4; ++j) { v[2 * j] = __builtin_bit_cast(float, raw[j] << 16); v[2 * j + 1] = __builtin_bit_cast(float, raw[j] & 0xffff0000u); }
;                 float sm = 0.f;
; #pragma unroll
;                 for (int j = 0; j < 8; ++j) sm += v[j];
;                 sm = row16_sum(sm);
;                 const float mu = sm * (1.0f / 128.0f);
;                 float sq = 0.f;
; #pragma unroll
;                 for (int j = 0; j < 8; ++j) { v[j] -= mu; sq += v[j] * v[j]; }
;                 sq = row16_sum(sq);
;                 const float rs = __builtin_amdgcn_rsqf(sq * (1.0f / 128.0f) + EPS);
; #pragma unroll
;                 for (int j = 0; j < 8; ++j) yv[j][i] = v[j] * rs * (j < 4 ? ga0[j & 3] : ga1[j & 3]) + (j < 4 ? be0[j & 3] : be1[j & 3]);
;             }
;             const int s0 = 64 * th + 16 * rr + 8 * hf;
;             LAS unsigned char* dst = lds + (gI * 128 + 8 * sub) * LDS_TT_PITCH + 16 * ((s0 >> 3) ^ sub);
; #pragma unroll
;             for (int j = 0; j < 8; ++j) {
;                 u32x4 w; w.x = pk2(yv[j][0], yv[j][1]); w.y = pk2(yv[j][2], yv[j][3]); w.z = pk2(yv[j][4], yv[j][5]); w.w = pk2(yv[j][6], yv[j][7]);
;                 *(LAS u32x4*)(dst + j * LDS_TT_PITCH) = w;
;             }
	v_cvt_pk_bf16_f32 v51, v96, v97
	v_cvt_pk_bf16_f32 v52, v60, v61
	v_cvt_pk_bf16_f32 v53, v130, v131
	ds_write_b128 v5, v[50:53] offset:1360
	v_cvt_pk_bf16_f32 v50, v82, v83
	v_cvt_pk_bf16_f32 v51, v72, v73
	v_cvt_pk_bf16_f32 v52, v120, v121
	v_cvt_pk_bf16_f32 v53, v132, v133
	v_lshlrev_b32_e32 v61, 16, v46
	v_lshlrev_b32_e32 v60, 16, v42
	ds_write_b128 v5, v[50:53] offset:1632
	v_cvt_pk_bf16_f32 v51, v62, v63
	v_cvt_pk_bf16_f32 v52, v64, v65
	v_and_b32_e32 v54, 0xffff0000, v45
	v_lshlrev_b32_e32 v59, 16, v49
	v_lshlrev_b32_e32 v58, 16, v45
	v_and_b32_e32 v55, 0xffff0000, v49
	v_and_b32_e32 v63, 0xffff0000, v46
	v_and_b32_e32 v62, 0xffff0000, v42
	v_lshlrev_b32_e32 v64, 16, v43
	v_and_b32_e32 v46, 0xffff0000, v43
	v_lshlrev_b32_e32 v43, 16, v48
	v_and_b32_e32 v45, 0xffff0000, v48
	v_pk_add_f32 v[48:49], v[60:61], 0 op_sel_hi:[1,0]
	v_lshlrev_b32_e32 v65, 16, v47
	v_pk_add_f32 v[48:49], v[48:49], v[62:63]
	v_and_b32_e32 v47, 0xffff0000, v47
	v_pk_add_f32 v[48:49], v[48:49], v[64:65]
	v_lshlrev_b32_e32 v42, 16, v44
	v_pk_add_f32 v[48:49], v[48:49], v[46:47]
	v_and_b32_e32 v44, 0xffff0000, v44
	v_pk_add_f32 v[48:49], v[48:49], v[42:43]
	v_cvt_pk_bf16_f32 v50, v70, v71
	v_pk_add_f32 v[48:49], v[48:49], v[44:45]
	v_mov_b32_e32 v72, v44
	v_pk_add_f32 v[48:49], v[48:49], v[58:59]
	v_mov_b32_e32 v73, v42
	v_pk_add_f32 v[48:49], v[48:49], v[54:55]
	v_mov_b32_e32 v84, v54
	v_mov_b32_e32 v85, v58
	v_mov_b32_dpp v70, v48 row_ror:8 row_mask:0xf bank_mask:0xf bound_ctrl:1
	v_mov_b32_dpp v71, v49 row_ror:8 row_mask:0xf bank_mask:0xf bound_ctrl:1
	v_pk_add_f32 v[48:49], v[48:49], v[70:71]
	v_mov_b32_e32 v42, v45
	v_mov_b32_e32 v58, v55
	v_mov_b32_dpp v70, v48 row_ror:4 row_mask:0xf bank_mask:0xf bound_ctrl:1
	v_mov_b32_dpp v71, v49 row_ror:4 row_mask:0xf bank_mask:0xf bound_ctrl:1
	v_pk_add_f32 v[48:49], v[48:49], v[70:71]
	v_cvt_pk_bf16_f32 v53, v56, v57
	ds_write_b128 v5, v[50:53] offset:1904
	v_mov_b32_dpp v70, v48 quad_perm:[2,3,0,1] row_mask:0xf bank_mask:0xf bound_ctrl:1
	v_mov_b32_dpp v71, v49 quad_perm:[2,3,0,1] row_mask:0xf bank_mask:0xf bound_ctrl:1
	v_pk_add_f32 v[48:49], v[48:49], v[70:71]
	v_and_b32_e32 v56, 0xffff0000, v37
	v_and_b32_e32 v57, 0xffff0000, v41
	v_mov_b32_dpp v70, v48 quad_perm:[1,0,3,2] row_mask:0xf bank_mask:0xf bound_ctrl:1
	v_mov_b32_dpp v71, v49 quad_perm:[1,0,3,2] row_mask:0xf bank_mask:0xf bound_ctrl:1
	v_pk_add_f32 v[48:49], v[48:49], v[70:71]
	v_mov_b32_e32 v90, v56
	v_pk_mul_f32 v[70:71], v[48:49], s[24:25] op_sel_hi:[1,0]
	v_pk_fma_f32 v[62:63], v[48:49], s[24:25], v[62:63] op_sel_hi:[1,0,1] neg_lo:[1,0,0] neg_hi:[1,0,0]
	v_pk_fma_f32 v[60:61], v[48:49], s[24:25], v[60:61] op_sel_hi:[1,0,1] neg_lo:[1,0,0] neg_hi:[1,0,0]
	v_pk_add_f32 v[72:73], v[72:73], v[70:71] op_sel_hi:[1,0] neg_lo:[0,1] neg_hi:[0,1]
	v_pk_add_f32 v[84:85], v[84:85], v[70:71] op_sel_hi:[1,0] neg_lo:[0,1] neg_hi:[0,1]
	v_pk_add_f32 v[42:43], v[42:43], v[70:71] op_sel:[0,1] neg_lo:[0,1] neg_hi:[0,1]
	v_pk_add_f32 v[58:59], v[58:59], v[70:71] op_sel:[0,1] neg_lo:[0,1] neg_hi:[0,1]
	v_pk_mul_f32 v[70:71], v[62:63], v[62:63]
	v_pk_fma_f32 v[64:65], v[48:49], s[24:25], v[64:65] op_sel_hi:[1,0,1] neg_lo:[1,0,0] neg_hi:[1,0,0]
	v_pk_fma_f32 v[70:71], v[60:61], v[60:61], v[70:71]
	v_pk_fma_f32 v[46:47], v[48:49], s[24:25], v[46:47] op_sel_hi:[1,0,1] neg_lo:[1,0,0] neg_hi:[1,0,0]
	v_pk_fma_f32 v[70:71], v[64:65], v[64:65], v[70:71]
	v_pk_mul_f32 v[82:83], v[72:73], v[72:73]
	v_pk_fma_f32 v[48:49], v[46:47], v[46:47], v[70:71]
	v_pk_mul_f32 v[86:87], v[84:85], v[84:85]
	v_add_f32_e32 v7, v83, v48
	v_add_f32_e32 v7, v82, v7
	v_add_f32_e32 v7, v87, v7
	v_add_f32_e32 v7, v86, v7
	v_pk_mul_f32 v[44:45], v[42:43], v[42:43]
	v_pk_mul_f32 v[54:55], v[58:59], v[58:59]
	v_add_f32_dpp v7, v7, v7 row_ror:8 row_mask:0xf bank_mask:0xf bound_ctrl:1
	s_nop 1
	v_add_f32_dpp v7, v7, v7 row_ror:4 row_mask:0xf bank_mask:0xf bound_ctrl:1
	s_nop 1
	v_add_f32_dpp v7, v7, v7 quad_perm:[2,3,0,1] row_mask:0xf bank_mask:0xf bound_ctrl:1
	s_nop 1
	v_add_f32_dpp v7, v7, v7 quad_perm:[1,0,3,2] row_mask:0xf bank_mask:0xf bound_ctrl:1
	v_fmamk_f32 v7, v7, 0x3c000000, v1
	v_rsq_f32_e32 v70, v7
	v_add_f32_e32 v7, v45, v49
	v_add_f32_e32 v7, v44, v7
	v_add_f32_e32 v7, v55, v7
	v_add_f32_e32 v7, v54, v7
	s_nop 1
	v_add_f32_dpp v7, v7, v7 row_ror:8 row_mask:0xf bank_mask:0xf bound_ctrl:1
	s_nop 1
	v_add_f32_dpp v7, v7, v7 row_ror:4 row_mask:0xf bank_mask:0xf bound_ctrl:1
	s_nop 1
	v_add_f32_dpp v7, v7, v7 quad_perm:[2,3,0,1] row_mask:0xf bank_mask:0xf bound_ctrl:1
	s_nop 1
	v_add_f32_dpp v7, v7, v7 quad_perm:[1,0,3,2] row_mask:0xf bank_mask:0xf bound_ctrl:1
	v_fmamk_f32 v7, v7, 0x3c000000, v1
	v_rsq_f32_e32 v71, v7
	s_nop 0
	v_pk_mul_f32 v[44:45], v[60:61], v[70:71]
	s_nop 0
	v_pk_fma_f32 v[54:55], v[10:11], v[44:45], v[14:15] op_sel_hi:[0,1,0]
	v_pk_mul_f32 v[44:45], v[62:63], v[70:71]
	v_lshlrev_b32_e32 v63, 16, v38
	v_pk_fma_f32 v[52:53], v[10:11], v[44:45], v[14:15] op_sel:[1,0,1]
	v_pk_mul_f32 v[44:45], v[64:65], v[70:71]
	v_lshlrev_b32_e32 v62, 16, v34
	v_pk_fma_f32 v[50:51], v[12:13], v[44:45], v[16:17] op_sel_hi:[0,1,0]
	v_pk_mul_f32 v[44:45], v[46:47], v[70:71]
	v_lshlrev_b32_e32 v61, 16, v41
	v_pk_fma_f32 v[48:49], v[74:75], v[44:45], v[76:77] op_sel_hi:[0,1,0]
	v_mov_b32_e32 v44, v73
	v_mov_b32_e32 v73, v42
	v_mov_b32_e32 v45, v43
	v_pk_mul_f32 v[42:43], v[72:73], v[70:71]
	v_lshlrev_b32_e32 v60, 16, v37
	v_and_b32_e32 v65, 0xffff0000, v38
	v_and_b32_e32 v64, 0xffff0000, v34
	v_lshlrev_b32_e32 v72, 16, v35
	v_and_b32_e32 v38, 0xffff0000, v35
	v_lshlrev_b32_e32 v35, 16, v40
	v_and_b32_e32 v37, 0xffff0000, v40
	v_pk_add_f32 v[40:41], v[62:63], 0 op_sel_hi:[1,0]
	v_lshlrev_b32_e32 v73, 16, v39
; __device__ __forceinline__ void gmlp_unit(const GmlpP& P, int b, int ch, LAS unsigned char* lds, int wave, int lane_in) {
;     ...
;             for (int i = 0; i < 8; ++i) {
;                 const u32x4 raw = rawv[8 * hf + i];
;                 float v[8];
; #pragma unroll
;                 for (int j = 0; j < 4; ++j) { v[2 * j] = __builtin_bit_cast(float, raw[j] << 16); v[2 * j + 1] = __builtin_bit_cast(float, raw[j] & 0xffff0000u); }
;                 float sm = 0.f;
; #pragma unroll
;                 for (int j = 0; j < 8; ++j) sm += v[j];
;                 sm = row16_sum(sm);
;                 const float mu = sm * (1.0f / 128.0f);
;                 float sq = 0.f;
; #pragma unroll
;                 for (int j = 0; j < 8; ++j) { v[j] -= mu; sq += v[j] * v[j]; }
;                 sq = row16_sum(sq);
;                 const float rs = __builtin_amdgcn_rsqf(sq * (1.0f / 128.0f) + EPS);
; #pragma unroll
;                 for (int j = 0; j < 8; ++j) yv[j][i] = v[j] * rs * (j < 4 ? ga0[j & 3] : ga1[j & 3]) + (j < 4 ? be0[j & 3] : be1[j & 3]);
;             }
	v_pk_add_f32 v[40:41], v[40:41], v[64:65]
	v_and_b32_e32 v39, 0xffff0000, v39
	v_pk_add_f32 v[40:41], v[40:41], v[72:73]
	v_lshlrev_b32_e32 v34, 16, v36
	v_pk_add_f32 v[40:41], v[40:41], v[38:39]
	v_and_b32_e32 v36, 0xffff0000, v36
	v_pk_add_f32 v[40:41], v[40:41], v[34:35]
	v_mov_b32_e32 v86, v36
	v_pk_add_f32 v[40:41], v[40:41], v[36:37]
	v_mov_b32_e32 v87, v34
	v_pk_add_f32 v[40:41], v[40:41], v[60:61]
	v_mov_b32_e32 v91, v60
	v_pk_add_f32 v[40:41], v[40:41], v[56:57]
	v_mov_b32_e32 v34, v37
	v_mov_b32_e32 v60, v57
	v_mov_b32_dpp v82, v40 row_ror:8 row_mask:0xf bank_mask:0xf bound_ctrl:1
	v_mov_b32_dpp v83, v41 row_ror:8 row_mask:0xf bank_mask:0xf bound_ctrl:1
	v_pk_add_f32 v[40:41], v[40:41], v[82:83]
	v_pk_mul_f32 v[44:45], v[44:45], v[70:71]
	s_nop 0
	v_mov_b32_dpp v82, v40 row_ror:4 row_mask:0xf bank_mask:0xf bound_ctrl:1
	v_mov_b32_dpp v83, v41 row_ror:4 row_mask:0xf bank_mask:0xf bound_ctrl:1
	v_pk_add_f32 v[40:41], v[40:41], v[82:83]
	v_pk_fma_f32 v[46:47], v[2:3], v[44:45], v[6:7] op_sel_hi:[0,1,0]
	v_pk_fma_f32 v[44:45], v[78:79], v[42:43], v[80:81] op_sel_hi:[0,1,0]
	v_mov_b32_dpp v82, v40 quad_perm:[2,3,0,1] row_mask:0xf bank_mask:0xf bound_ctrl:1
	v_mov_b32_dpp v83, v41 quad_perm:[2,3,0,1] row_mask:0xf bank_mask:0xf bound_ctrl:1
	v_pk_add_f32 v[40:41], v[40:41], v[82:83]
	v_mov_b32_e32 v42, v85
	v_mov_b32_e32 v43, v59
	v_mov_b32_dpp v82, v40 quad_perm:[1,0,3,2] row_mask:0xf bank_mask:0xf bound_ctrl:1
	v_mov_b32_dpp v83, v41 quad_perm:[1,0,3,2] row_mask:0xf bank_mask:0xf bound_ctrl:1
	v_pk_add_f32 v[40:41], v[40:41], v[82:83]
	v_pk_mul_f32 v[42:43], v[42:43], v[70:71]
	v_pk_mul_f32 v[82:83], v[40:41], s[24:25] op_sel_hi:[1,0]
	v_pk_fma_f32 v[62:63], v[40:41], s[24:25], v[62:63] op_sel_hi:[1,0,1] neg_lo:[1,0,0] neg_hi:[1,0,0]
	v_pk_add_f32 v[86:87], v[86:87], v[82:83] op_sel_hi:[1,0] neg_lo:[0,1] neg_hi:[0,1]
	v_pk_add_f32 v[90:91], v[90:91], v[82:83] op_sel_hi:[1,0] neg_lo:[0,1] neg_hi:[0,1]
	v_pk_add_f32 v[36:37], v[34:35], v[82:83] op_sel:[0,1] neg_lo:[0,1] neg_hi:[0,1]
	v_pk_add_f32 v[82:83], v[60:61], v[82:83] op_sel:[0,1] neg_lo:[0,1] neg_hi:[0,1]
	v_pk_fma_f32 v[60:61], v[40:41], s[24:25], v[64:65] op_sel_hi:[1,0,1] neg_lo:[1,0,0] neg_hi:[1,0,0]
	v_pk_fma_f32 v[72:73], v[40:41], s[24:25], v[72:73] op_sel_hi:[1,0,1] neg_lo:[1,0,0] neg_hi:[1,0,0]
	v_pk_mul_f32 v[64:65], v[60:61], v[60:61]
	v_pk_fma_f32 v[38:39], v[40:41], s[24:25], v[38:39] op_sel_hi:[1,0,1] neg_lo:[1,0,0] neg_hi:[1,0,0]
	v_pk_fma_f32 v[64:65], v[62:63], v[62:63], v[64:65]
	v_pk_mul_f32 v[88:89], v[86:87], v[86:87]
	v_pk_fma_f32 v[64:65], v[72:73], v[72:73], v[64:65]
	v_pk_fma_f32 v[42:43], v[4:5], v[42:43], v[8:9] op_sel_hi:[0,1,0]
	v_pk_fma_f32 v[40:41], v[38:39], v[38:39], v[64:65]
	v_pk_mul_f32 v[92:93], v[90:91], v[90:91]
	v_add_f32_e32 v5, v89, v40
	v_add_f32_e32 v5, v88, v5
	v_add_f32_e32 v5, v93, v5
	v_add_f32_e32 v5, v92, v5
	v_pk_mul_f32 v[34:35], v[36:37], v[36:37]
	v_pk_mul_f32 v[56:57], v[82:83], v[82:83]
	v_add_f32_dpp v5, v5, v5 row_ror:8 row_mask:0xf bank_mask:0xf bound_ctrl:1
	v_mov_b32_e32 v85, v58
	v_lshlrev_b32_e32 v88, 16, v27
	v_add_f32_dpp v5, v5, v5 row_ror:4 row_mask:0xf bank_mask:0xf bound_ctrl:1
	v_lshlrev_b32_e32 v89, 16, v31
	v_and_b32_e32 v31, 0xffff0000, v31
	v_add_f32_dpp v5, v5, v5 quad_perm:[2,3,0,1] row_mask:0xf bank_mask:0xf bound_ctrl:1
	s_nop 1
	v_add_f32_dpp v5, v5, v5 quad_perm:[1,0,3,2] row_mask:0xf bank_mask:0xf bound_ctrl:1
	v_fmamk_f32 v5, v5, 0x3c000000, v1
	v_rsq_f32_e32 v64, v5
	v_add_f32_e32 v5, v35, v41
	v_add_f32_e32 v5, v34, v5
	v_add_f32_e32 v5, v57, v5
	v_add_f32_e32 v5, v56, v5
	v_pk_mul_f32 v[34:35], v[84:85], v[70:71]
	v_lshlrev_b32_e32 v85, 16, v30
	v_add_f32_dpp v5, v5, v5 row_ror:8 row_mask:0xf bank_mask:0xf bound_ctrl:1
	v_lshlrev_b32_e32 v84, 16, v26
	v_and_b32_e32 v70, 0xffff0000, v29
	v_add_f32_dpp v5, v5, v5 row_ror:4 row_mask:0xf bank_mask:0xf bound_ctrl:1
	v_and_b32_e32 v71, 0xffff0000, v33
	v_mov_b32_e32 v98, v70
	v_add_f32_dpp v5, v5, v5 quad_perm:[2,3,0,1] row_mask:0xf bank_mask:0xf bound_ctrl:1
	v_pk_fma_f32 v[34:35], v[66:67], v[34:35], v[68:69] op_sel_hi:[0,1,0]
	s_nop 0
	v_add_f32_dpp v5, v5, v5 quad_perm:[1,0,3,2] row_mask:0xf bank_mask:0xf bound_ctrl:1
	v_fmamk_f32 v5, v5, 0x3c000000, v1
	v_rsq_f32_e32 v65, v5
	s_nop 0
	v_pk_mul_f32 v[40:41], v[62:63], v[64:65]
	v_pk_mul_f32 v[38:39], v[38:39], v[64:65]
	v_pk_fma_f32 v[62:63], v[10:11], v[40:41], v[14:15] op_sel_hi:[0,1,0]
	v_pk_mul_f32 v[40:41], v[60:61], v[64:65]
	v_pk_fma_f32 v[56:57], v[74:75], v[38:39], v[76:77] op_sel_hi:[0,1,0]
	v_mov_b32_e32 v38, v87
	v_mov_b32_e32 v87, v36
	v_pk_fma_f32 v[60:61], v[10:11], v[40:41], v[14:15] op_sel:[1,0,1]
	v_pk_mul_f32 v[40:41], v[72:73], v[64:65]
	v_mov_b32_e32 v39, v37
	v_pk_mul_f32 v[36:37], v[86:87], v[64:65]
	v_lshlrev_b32_e32 v73, 16, v33
	v_lshlrev_b32_e32 v72, 16, v29
	v_and_b32_e32 v87, 0xffff0000, v30
	v_and_b32_e32 v86, 0xffff0000, v26
	v_and_b32_e32 v30, 0xffff0000, v27
	v_lshlrev_b32_e32 v27, 16, v32
	v_and_b32_e32 v29, 0xffff0000, v32
	v_pk_add_f32 v[32:33], v[84:85], 0 op_sel_hi:[1,0]
	v_lshlrev_b32_e32 v26, 16, v28
	v_pk_add_f32 v[32:33], v[32:33], v[86:87]
	v_and_b32_e32 v28, 0xffff0000, v28
	v_pk_add_f32 v[32:33], v[32:33], v[88:89]
	v_mov_b32_e32 v94, v28
	v_pk_add_f32 v[32:33], v[32:33], v[30:31]
	v_mov_b32_e32 v95, v26
	v_pk_add_f32 v[32:33], v[32:33], v[26:27]
	v_mov_b32_e32 v99, v72
	v_pk_add_f32 v[32:33], v[32:33], v[28:29]
	v_mov_b32_e32 v26, v29
	v_pk_add_f32 v[32:33], v[32:33], v[72:73]
	v_mov_b32_e32 v72, v71
	v_pk_add_f32 v[32:33], v[32:33], v[70:71]
	v_pk_mul_f32 v[38:39], v[38:39], v[64:65]
	v_pk_fma_f32 v[58:59], v[12:13], v[40:41], v[16:17] op_sel_hi:[0,1,0]
; __device__ __forceinline__ void gmlp_unit(const GmlpP& P, int b, int ch, LAS unsigned char* lds, int wave, int lane_in) {
;     ...
;             for (int i = 0; i < 8; ++i) {
;                 const u32x4 raw = rawv[8 * hf + i];
;                 float v[8];
; #pragma unroll
;                 for (int j = 0; j < 4; ++j) { v[2 * j] = __builtin_bit_cast(float, raw[j] << 16); v[2 * j + 1] = __builtin_bit_cast(float, raw[j] & 0xffff0000u); }
;                 float sm = 0.f;
; #pragma unroll
;                 for (int j = 0; j < 8; ++j) sm += v[j];
;                 sm = row16_sum(sm);
;                 const float mu = sm * (1.0f / 128.0f);
;                 float sq = 0.f;
; #pragma unroll
;                 for (int j = 0; j < 8; ++j) { v[j] -= mu; sq += v[j] * v[j]; }
;                 sq = row16_sum(sq);
;                 const float rs = __builtin_amdgcn_rsqf(sq * (1.0f / 128.0f) + EPS);
; #pragma unroll
;                 for (int j = 0; j < 8; ++j) yv[j][i] = v[j] * rs * (j < 4 ? ga0[j & 3] : ga1[j & 3]) + (j < 4 ? be0[j & 3] : be1[j & 3]);
;             }
	v_mov_b32_dpp v92, v32 row_ror:8 row_mask:0xf bank_mask:0xf bound_ctrl:1
	v_mov_b32_dpp v93, v33 row_ror:8 row_mask:0xf bank_mask:0xf bound_ctrl:1
	v_pk_add_f32 v[32:33], v[32:33], v[92:93]
	v_pk_fma_f32 v[40:41], v[2:3], v[38:39], v[6:7] op_sel_hi:[0,1,0]
	v_pk_fma_f32 v[38:39], v[78:79], v[36:37], v[80:81] op_sel_hi:[0,1,0]
	v_mov_b32_dpp v92, v32 row_ror:4 row_mask:0xf bank_mask:0xf bound_ctrl:1
	v_mov_b32_dpp v93, v33 row_ror:4 row_mask:0xf bank_mask:0xf bound_ctrl:1
	v_pk_add_f32 v[32:33], v[32:33], v[92:93]
	v_mov_b32_e32 v36, v91
	v_mov_b32_e32 v37, v83
	v_mov_b32_dpp v92, v32 quad_perm:[2,3,0,1] row_mask:0xf bank_mask:0xf bound_ctrl:1
	v_mov_b32_dpp v93, v33 quad_perm:[2,3,0,1] row_mask:0xf bank_mask:0xf bound_ctrl:1
	v_pk_add_f32 v[32:33], v[32:33], v[92:93]
	v_pk_mul_f32 v[36:37], v[36:37], v[64:65]
	v_mov_b32_e32 v91, v82
	v_mov_b32_dpp v92, v32 quad_perm:[1,0,3,2] row_mask:0xf bank_mask:0xf bound_ctrl:1
	v_mov_b32_dpp v93, v33 quad_perm:[1,0,3,2] row_mask:0xf bank_mask:0xf bound_ctrl:1
	v_pk_add_f32 v[32:33], v[32:33], v[92:93]
	v_pk_fma_f32 v[36:37], v[4:5], v[36:37], v[8:9] op_sel_hi:[0,1,0]
	v_pk_mul_f32 v[92:93], v[32:33], s[24:25] op_sel_hi:[1,0]
	v_pk_fma_f32 v[86:87], v[32:33], s[24:25], v[86:87] op_sel_hi:[1,0,1] neg_lo:[1,0,0] neg_hi:[1,0,0]
	v_pk_fma_f32 v[84:85], v[32:33], s[24:25], v[84:85] op_sel_hi:[1,0,1] neg_lo:[1,0,0] neg_hi:[1,0,0]
	v_pk_add_f32 v[94:95], v[94:95], v[92:93] op_sel_hi:[1,0] neg_lo:[0,1] neg_hi:[0,1]
	v_pk_add_f32 v[98:99], v[98:99], v[92:93] op_sel_hi:[1,0] neg_lo:[0,1] neg_hi:[0,1]
	v_pk_add_f32 v[26:27], v[26:27], v[92:93] op_sel:[0,1] neg_lo:[0,1] neg_hi:[0,1]
	v_pk_add_f32 v[70:71], v[72:73], v[92:93] op_sel:[0,1] neg_lo:[0,1] neg_hi:[0,1]
	v_pk_mul_f32 v[92:93], v[86:87], v[86:87]
	v_pk_fma_f32 v[88:89], v[32:33], s[24:25], v[88:89] op_sel_hi:[1,0,1] neg_lo:[1,0,0] neg_hi:[1,0,0]
	v_pk_fma_f32 v[92:93], v[84:85], v[84:85], v[92:93]
	v_pk_fma_f32 v[30:31], v[32:33], s[24:25], v[30:31] op_sel_hi:[1,0,1] neg_lo:[1,0,0] neg_hi:[1,0,0]
	v_pk_fma_f32 v[92:93], v[88:89], v[88:89], v[92:93]
	v_pk_mul_f32 v[96:97], v[94:95], v[94:95]
	v_pk_fma_f32 v[32:33], v[30:31], v[30:31], v[92:93]
	v_pk_mul_f32 v[100:101], v[98:99], v[98:99]
	v_add_f32_e32 v5, v97, v32
	v_add_f32_e32 v5, v96, v5
	v_add_f32_e32 v5, v101, v5
	v_add_f32_e32 v5, v100, v5
	v_pk_mul_f32 v[28:29], v[26:27], v[26:27]
	v_pk_mul_f32 v[72:73], v[70:71], v[70:71]
	v_add_f32_dpp v5, v5, v5 row_ror:8 row_mask:0xf bank_mask:0xf bound_ctrl:1
	v_lshlrev_b32_e32 v93, 16, v22
	v_lshlrev_b32_e32 v92, 16, v18
	v_add_f32_dpp v5, v5, v5 row_ror:4 row_mask:0xf bank_mask:0xf bound_ctrl:1
	v_lshlrev_b32_e32 v96, 16, v19
	v_lshlrev_b32_e32 v97, 16, v23
	v_add_f32_dpp v5, v5, v5 quad_perm:[2,3,0,1] row_mask:0xf bank_mask:0xf bound_ctrl:1
	v_and_b32_e32 v23, 0xffff0000, v23
	s_nop 0
	v_add_f32_dpp v5, v5, v5 quad_perm:[1,0,3,2] row_mask:0xf bank_mask:0xf bound_ctrl:1
	v_fmamk_f32 v5, v5, 0x3c000000, v1
	v_rsq_f32_e32 v32, v5
	v_add_f32_e32 v5, v29, v33
	v_add_f32_e32 v5, v28, v5
	v_add_f32_e32 v5, v73, v5
	v_add_f32_e32 v5, v72, v5
	v_pk_mul_f32 v[28:29], v[90:91], v[64:65]
	v_lshlrev_b32_e32 v91, 16, v25
	v_add_f32_dpp v5, v5, v5 row_ror:8 row_mask:0xf bank_mask:0xf bound_ctrl:1
	v_lshlrev_b32_e32 v90, 16, v21
	v_mov_b32_e32 v107, v90
	v_add_f32_dpp v5, v5, v5 row_ror:4 row_mask:0xf bank_mask:0xf bound_ctrl:1
	v_pk_fma_f32 v[28:29], v[66:67], v[28:29], v[68:69] op_sel_hi:[0,1,0]
	s_nop 0
	v_add_f32_dpp v5, v5, v5 quad_perm:[2,3,0,1] row_mask:0xf bank_mask:0xf bound_ctrl:1
	s_nop 1
	v_add_f32_dpp v5, v5, v5 quad_perm:[1,0,3,2] row_mask:0xf bank_mask:0xf bound_ctrl:1
	v_fmamk_f32 v5, v5, 0x3c000000, v1
	v_rsq_f32_e32 v33, v5
	s_nop 0
	v_pk_mul_f32 v[64:65], v[84:85], v[32:33]
	v_mov_b32_e32 v84, v95
	v_mov_b32_e32 v95, v26
	v_pk_mul_f32 v[82:83], v[88:89], v[32:33]
	v_mov_b32_e32 v85, v27
	v_pk_mul_f32 v[26:27], v[94:95], v[32:33]
	v_and_b32_e32 v88, 0xffff0000, v21
	v_and_b32_e32 v89, 0xffff0000, v25
	v_and_b32_e32 v95, 0xffff0000, v22
	v_and_b32_e32 v94, 0xffff0000, v18
	v_and_b32_e32 v22, 0xffff0000, v19
	v_lshlrev_b32_e32 v19, 16, v24
	v_and_b32_e32 v21, 0xffff0000, v24
	v_pk_add_f32 v[24:25], v[92:93], 0 op_sel_hi:[1,0]
	v_lshlrev_b32_e32 v18, 16, v20
	v_pk_add_f32 v[24:25], v[24:25], v[94:95]
	v_and_b32_e32 v20, 0xffff0000, v20
	v_pk_add_f32 v[24:25], v[24:25], v[96:97]
	v_mov_b32_e32 v102, v20
	v_pk_add_f32 v[24:25], v[24:25], v[22:23]
	v_mov_b32_e32 v103, v18
	v_pk_add_f32 v[24:25], v[24:25], v[18:19]
	v_mov_b32_e32 v106, v88
	v_pk_add_f32 v[24:25], v[24:25], v[20:21]
	v_mov_b32_e32 v18, v21
	v_pk_add_f32 v[24:25], v[24:25], v[90:91]
	v_mov_b32_e32 v90, v89
	v_pk_add_f32 v[24:25], v[24:25], v[88:89]
	v_pk_mul_f32 v[72:73], v[86:87], v[32:33]
	v_mov_b32_e32 v86, v99
	v_mov_b32_dpp v100, v24 row_ror:8 row_mask:0xf bank_mask:0xf bound_ctrl:1
	v_mov_b32_dpp v101, v25 row_ror:8 row_mask:0xf bank_mask:0xf bound_ctrl:1
	v_pk_add_f32 v[24:25], v[24:25], v[100:101]
	v_mov_b32_e32 v87, v71
	v_pk_mul_f32 v[86:87], v[86:87], v[32:33]
	v_mov_b32_dpp v100, v24 row_ror:4 row_mask:0xf bank_mask:0xf bound_ctrl:1
	v_mov_b32_dpp v101, v25 row_ror:4 row_mask:0xf bank_mask:0xf bound_ctrl:1
	v_pk_add_f32 v[24:25], v[24:25], v[100:101]
	v_pk_fma_f32 v[86:87], v[4:5], v[86:87], v[8:9] op_sel_hi:[0,1,0]
	v_mov_b32_e32 v99, v70
	v_mov_b32_dpp v100, v24 quad_perm:[2,3,0,1] row_mask:0xf bank_mask:0xf bound_ctrl:1
	v_mov_b32_dpp v101, v25 quad_perm:[2,3,0,1] row_mask:0xf bank_mask:0xf bound_ctrl:1
	v_pk_add_f32 v[24:25], v[24:25], v[100:101]
	v_pk_mul_f32 v[30:31], v[30:31], v[32:33]
	v_pk_mul_f32 v[84:85], v[84:85], v[32:33]
	v_mov_b32_dpp v100, v24 quad_perm:[1,0,3,2] row_mask:0xf bank_mask:0xf bound_ctrl:1
; #define LAS __attribute__((address_space(3)))
; __device__ __forceinline__ unsigned pk2(float lo, float hi) { f32x2 v = {lo, hi}; bf16x2_t b = __builtin_convertvector(v, bf16x2_t); return __builtin_bit_cast(unsigned, b); }
; __device__ __forceinline__ void gmlp_unit(const GmlpP& P, int b, int ch, LAS unsigned char* lds, int wave, int lane_in) {
;     ...
;             for (int i = 0; i < 8; ++i) {
;                 const u32x4 raw = rawv[8 * hf + i];
;                 float v[8];
; #pragma unroll
;                 for (int j = 0; j < 4; ++j) { v[2 * j] = __builtin_bit_cast(float, raw[j] << 16); v[2 * j + 1] = __builtin_bit_cast(float, raw[j] & 0xffff0000u); }
;                 float sm = 0.f;
; #pragma unroll
;                 for (int j = 0; j < 8; ++j) sm += v[j];
;                 sm = row16_sum(sm);
;                 const float mu = sm * (1.0f / 128.0f);
;                 float sq = 0.f;
; #pragma unroll
;                 for (int j = 0; j < 8; ++j) { v[j] -= mu; sq += v[j] * v[j]; }
;                 sq = row16_sum(sq);
;                 const float rs = __builtin_amdgcn_rsqf(sq * (1.0f / 128.0f) + EPS);
; #pragma unroll
;                 for (int j = 0; j < 8; ++j) yv[j][i] = v[j] * rs * (j < 4 ? ga0[j & 3] : ga1[j & 3]) + (j < 4 ? be0[j & 3] : be1[j & 3]);
;             }
;             const int s0 = 64 * th + 16 * rr + 8 * hf;
;             LAS unsigned char* dst = lds + (gI * 128 + 8 * sub) * LDS_TT_PITCH + 16 * ((s0 >> 3) ^ sub);
; #pragma unroll
;             for (int j = 0; j < 8; ++j) {
;                 u32x4 w; w.x = pk2(yv[j][0], yv[j][1]); w.y = pk2(yv[j][2], yv[j][3]); w.z = pk2(yv[j][4], yv[j][5]); w.w = pk2(yv[j][6], yv[j][7]);
;                 *(LAS u32x4*)(dst + j * LDS_TT_PITCH) = w;
;             }
;             asm volatile("" ::: "memory");
;         }
;     }
;     const int r32 = lane & 31, h = lane >> 5;
;     const int tt0 = th, tt1 = 3 - th;
;     bf16x8 bw0[4], bw1[8];
;     { const bf16_t* w0p = P.wsb + ((size_t)(gI * 128 + 32 * tt0 + r32) * 128 + 8 * h);
;       const bf16_t* w1p = P.wsb + ((size_t)(gI * 128 + 32 * tt1 + r32) * 128 + 8 * h);
; #pragma unroll
;       for (int ks = 0; ks < 4; ++ks) bw0[ks] = *(const bf16x8*)(w0p + 16 * ks);
; #pragma unroll
;       for (int ks = 0; ks < 8; ++ks) bw1[ks] = *(const bf16x8*)(w1p + 16 * ks); }
;     __syncthreads();
	v_mov_b32_dpp v101, v25 quad_perm:[1,0,3,2] row_mask:0xf bank_mask:0xf bound_ctrl:1
	v_pk_add_f32 v[24:25], v[24:25], v[100:101]
	v_pk_fma_f32 v[64:65], v[10:11], v[64:65], v[14:15] op_sel_hi:[0,1,0]
	v_pk_mul_f32 v[100:101], v[24:25], s[24:25] op_sel_hi:[1,0]
	v_pk_fma_f32 v[94:95], v[24:25], s[24:25], v[94:95] op_sel_hi:[1,0,1] neg_lo:[1,0,0] neg_hi:[1,0,0]
	v_pk_fma_f32 v[92:93], v[24:25], s[24:25], v[92:93] op_sel_hi:[1,0,1] neg_lo:[1,0,0] neg_hi:[1,0,0]
	v_pk_add_f32 v[102:103], v[102:103], v[100:101] op_sel_hi:[1,0] neg_lo:[0,1] neg_hi:[0,1]
	v_pk_add_f32 v[106:107], v[106:107], v[100:101] op_sel_hi:[1,0] neg_lo:[0,1] neg_hi:[0,1]
	v_pk_add_f32 v[18:19], v[18:19], v[100:101] op_sel:[0,1] neg_lo:[0,1] neg_hi:[0,1]
	v_pk_add_f32 v[88:89], v[90:91], v[100:101] op_sel:[0,1] neg_lo:[0,1] neg_hi:[0,1]
	v_pk_mul_f32 v[100:101], v[94:95], v[94:95]
	v_pk_fma_f32 v[96:97], v[24:25], s[24:25], v[96:97] op_sel_hi:[1,0,1] neg_lo:[1,0,0] neg_hi:[1,0,0]
	v_pk_fma_f32 v[100:101], v[92:93], v[92:93], v[100:101]
	v_pk_fma_f32 v[22:23], v[24:25], s[24:25], v[22:23] op_sel_hi:[1,0,1] neg_lo:[1,0,0] neg_hi:[1,0,0]
	v_pk_fma_f32 v[100:101], v[96:97], v[96:97], v[100:101]
	v_pk_mul_f32 v[104:105], v[102:103], v[102:103]
	v_pk_fma_f32 v[24:25], v[22:23], v[22:23], v[100:101]
	v_pk_mul_f32 v[110:111], v[106:107], v[106:107]
	v_add_f32_e32 v5, v105, v24
	v_add_f32_e32 v5, v104, v5
	v_add_f32_e32 v5, v111, v5
	v_add_f32_e32 v5, v110, v5
	v_pk_mul_f32 v[20:21], v[18:19], v[18:19]
	v_pk_mul_f32 v[90:91], v[88:89], v[88:89]
	v_add_f32_dpp v5, v5, v5 row_ror:8 row_mask:0xf bank_mask:0xf bound_ctrl:1
	v_pk_fma_f32 v[72:73], v[10:11], v[72:73], v[14:15] op_sel:[1,0,1]
	v_pk_fma_f32 v[82:83], v[12:13], v[82:83], v[16:17] op_sel_hi:[0,1,0]
	v_add_f32_dpp v5, v5, v5 row_ror:4 row_mask:0xf bank_mask:0xf bound_ctrl:1
	v_pk_fma_f32 v[84:85], v[2:3], v[84:85], v[6:7] op_sel_hi:[0,1,0]
	v_pk_fma_f32 v[30:31], v[74:75], v[30:31], v[76:77] op_sel_hi:[0,1,0]
	v_add_f32_dpp v5, v5, v5 quad_perm:[2,3,0,1] row_mask:0xf bank_mask:0xf bound_ctrl:1
	v_pk_fma_f32 v[26:27], v[78:79], v[26:27], v[80:81] op_sel_hi:[0,1,0]
	s_nop 0
	v_add_f32_dpp v5, v5, v5 quad_perm:[1,0,3,2] row_mask:0xf bank_mask:0xf bound_ctrl:1
	v_fmamk_f32 v5, v5, 0x3c000000, v1
	v_rsq_f32_e32 v24, v5
	v_add_f32_e32 v5, v21, v25
	v_add_f32_e32 v5, v20, v5
	v_add_f32_e32 v5, v91, v5
	v_add_f32_e32 v5, v90, v5
	v_pk_mul_f32 v[20:21], v[98:99], v[32:33]
	s_nop 0
	v_add_f32_dpp v5, v5, v5 row_ror:8 row_mask:0xf bank_mask:0xf bound_ctrl:1
	v_pk_fma_f32 v[20:21], v[66:67], v[20:21], v[68:69] op_sel_hi:[0,1,0]
	s_nop 0
	v_add_f32_dpp v5, v5, v5 row_ror:4 row_mask:0xf bank_mask:0xf bound_ctrl:1
	s_nop 1
	v_add_f32_dpp v5, v5, v5 quad_perm:[2,3,0,1] row_mask:0xf bank_mask:0xf bound_ctrl:1
	s_nop 1
	v_add_f32_dpp v5, v5, v5 quad_perm:[1,0,3,2] row_mask:0xf bank_mask:0xf bound_ctrl:1
	v_fmamk_f32 v5, v5, 0x3c000000, v1
	v_rsq_f32_e32 v25, v5
	s_nop 0
	v_pk_mul_f32 v[32:33], v[92:93], v[24:25]
	v_pk_mul_f32 v[70:71], v[94:95], v[24:25]
	v_pk_fma_f32 v[32:33], v[10:11], v[32:33], v[14:15] op_sel_hi:[0,1,0]
	v_pk_fma_f32 v[10:11], v[10:11], v[70:71], v[14:15] op_sel:[1,0,1]
	v_pk_mul_f32 v[14:15], v[96:97], v[24:25]
	s_nop 0
	v_pk_fma_f32 v[12:13], v[12:13], v[14:15], v[16:17] op_sel_hi:[0,1,0]
	v_mov_b32_e32 v16, v103
	v_mov_b32_e32 v17, v19
	v_mov_b32_e32 v103, v18
	v_mov_b32_e32 v18, v107
	v_mov_b32_e32 v19, v89
	v_pk_mul_f32 v[16:17], v[16:17], v[24:25]
	v_pk_mul_f32 v[18:19], v[18:19], v[24:25]
	v_mov_b32_e32 v107, v88
	v_pk_fma_f32 v[6:7], v[2:3], v[16:17], v[6:7] op_sel_hi:[0,1,0]
	v_pk_fma_f32 v[8:9], v[4:5], v[18:19], v[8:9] op_sel_hi:[0,1,0]
	v_pk_mul_f32 v[4:5], v[106:107], v[24:25]
	v_bitop3_b32 v2, v3, v108, 1 bitop3:0x36
	v_pk_mul_f32 v[14:15], v[22:23], v[24:25]
	v_pk_fma_f32 v[18:19], v[66:67], v[4:5], v[68:69] op_sel_hi:[0,1,0]
	v_lshl_add_u32 v22, v2, 4, v75
	v_cvt_pk_bf16_f32 v2, v54, v55
	v_cvt_pk_bf16_f32 v3, v62, v63
	v_cvt_pk_bf16_f32 v4, v64, v65
	v_cvt_pk_bf16_f32 v5, v32, v33
	ds_write_b128 v22, v[2:5]
	v_cvt_pk_bf16_f32 v2, v52, v53
	v_cvt_pk_bf16_f32 v3, v60, v61
	v_cvt_pk_bf16_f32 v4, v72, v73
	v_cvt_pk_bf16_f32 v5, v10, v11
	v_pk_fma_f32 v[14:15], v[74:75], v[14:15], v[76:77] op_sel_hi:[0,1,0]
	ds_write_b128 v22, v[2:5] offset:272
	v_cvt_pk_bf16_f32 v2, v50, v51
	v_cvt_pk_bf16_f32 v3, v58, v59
	v_cvt_pk_bf16_f32 v4, v82, v83
	v_cvt_pk_bf16_f32 v5, v12, v13
	v_pk_mul_f32 v[16:17], v[102:103], v[24:25]
	ds_write_b128 v22, v[2:5] offset:544
	v_cvt_pk_bf16_f32 v2, v48, v49
	v_cvt_pk_bf16_f32 v3, v56, v57
	v_cvt_pk_bf16_f32 v4, v30, v31
	v_cvt_pk_bf16_f32 v5, v14, v15
	v_pk_fma_f32 v[16:17], v[78:79], v[16:17], v[80:81] op_sel_hi:[0,1,0]
	ds_write_b128 v22, v[2:5] offset:816
	v_cvt_pk_bf16_f32 v2, v46, v47
	v_cvt_pk_bf16_f32 v3, v40, v41
	v_cvt_pk_bf16_f32 v4, v84, v85
	v_cvt_pk_bf16_f32 v5, v6, v7
	ds_write_b128 v22, v[2:5] offset:1088
	v_cvt_pk_bf16_f32 v2, v44, v45
	v_cvt_pk_bf16_f32 v3, v38, v39
	v_cvt_pk_bf16_f32 v4, v26, v27
	v_cvt_pk_bf16_f32 v5, v16, v17
	ds_write_b128 v22, v[2:5] offset:1360
	v_cvt_pk_bf16_f32 v2, v42, v43
	v_cvt_pk_bf16_f32 v3, v36, v37
	v_cvt_pk_bf16_f32 v4, v86, v87
	v_cvt_pk_bf16_f32 v5, v8, v9
	ds_write_b128 v22, v[2:5] offset:1632
	v_cvt_pk_bf16_f32 v2, v34, v35
	v_cvt_pk_bf16_f32 v3, v28, v29
	v_cvt_pk_bf16_f32 v4, v20, v21
	v_cvt_pk_bf16_f32 v5, v18, v19
	ds_write_b128 v22, v[2:5] offset:1904
	v_or_b32_e32 v2, s22, v154
	v_ashrrev_i32_e32 v3, 31, v2
	v_lshlrev_b32_e32 v4, 3, v140
	v_ashrrev_i32_e32 v5, 31, v4
	v_lshlrev_b64 v[2:3], 8, v[2:3]
	v_lshl_add_u64 v[2:3], s[0:1], 0, v[2:3]
	v_lshlrev_b64 v[6:7], 1, v[4:5]
	v_lshl_add_u64 v[10:11], v[2:3], 0, v[6:7]
	global_load_dwordx4 v[2:5], v[10:11], off
	v_or_b32_e32 v8, s25, v154
	v_ashrrev_i32_e32 v9, 31, v8
	v_lshlrev_b64 v[8:9], 8, v[8:9]
	v_lshl_add_u64 v[8:9], s[0:1], 0, v[8:9]
	v_lshl_add_u64 v[12:13], v[8:9], 0, v[6:7]
	global_load_dwordx4 v[6:9], v[12:13], off
	global_load_dwordx4 v[144:147], v[10:11], off offset:32
	global_load_dwordx4 v[148:151], v[10:11], off offset:64
	global_load_dwordx4 v[156:159], v[10:11], off offset:96
	global_load_dwordx4 v[160:163], v[12:13], off offset:32
	global_load_dwordx4 v[164:167], v[12:13], off offset:64
	global_load_dwordx4 v[168:171], v[12:13], off offset:96
	global_load_dwordx4 v[172:175], v[12:13], off offset:128
	global_load_dwordx4 v[176:179], v[12:13], off offset:160
	global_load_dwordx4 v[134:137], v[12:13], off offset:192
	global_load_dwordx4 v[130:133], v[12:13], off offset:224
	v_or_b32_e32 v14, 32, v154
	v_or_b32_e32 v10, s6, v154
	v_or_b32_e32 v15, s6, v14
	v_mul_lo_u32 v10, v10, s48
	v_mul_lo_u32 v15, v15, s48
	v_lshrrev_b32_e32 v190, 3, v14
	v_add_u32_e32 v155, 0, v10
	v_xor_b32_e32 v10, v188, v140
	v_add_u32_e32 v189, 0, v15
	v_xor_b32_e32 v14, v190, v140
	v_lshl_add_u32 v10, v10, 4, v155
	v_lshl_add_u32 v14, v14, 4, v189
	s_waitcnt lgkmcnt(0)
	s_barrier
; #define LAS __attribute__((address_space(3)))
; __device__ __forceinline__ void gmlp_unit(const GmlpP& P, int b, int ch, LAS unsigned char* lds, int wave, int lane_in) {
;     ...
;     {
; #pragma unroll
;         for (int ks = 0; ks < 8; ++ks)
; #pragma unroll
;             for (int mt = 0; mt < 4; ++mt) {
;                 const int cc = 32 * mt + r32;
;                 const bf16x8 a = *(const LAS bf16x8*)(lds + (gI * 128 + cc) * LDS_TT_PITCH + 16 * ((2 * ks + h) ^ ((cc >> 3) & 15)));
;                 if (ks < 4) acc[mt][0] = __builtin_amdgcn_mfma_f32_32x32x16_bf16(a, bw0[ks], acc[mt][0], 0, 0, 0);
;                 acc[mt][1] = __builtin_amdgcn_mfma_f32_32x32x16_bf16(a, bw1[ks], acc[mt][1], 0, 0, 0);
;                 if (mt == 3 && (ks & 1)) asm volatile("" ::: "memory");
;             }
;     }
	ds_read_b128 v[10:13], v10
	ds_read_b128 v[14:17], v14
	s_waitcnt vmcnt(11) lgkmcnt(1)
	v_mfma_f32_32x32x16_bf16 v[114:129], v[10:13], v[2:5], 0
	v_lshl_add_u32 v153, v153, 4, v155
	ds_read_b128 v[180:183], v153
	v_xor_b32_e32 v153, v190, v152
	v_lshl_add_u32 v153, v153, 4, v189
	ds_read_b128 v[184:187], v153
	s_waitcnt vmcnt(10)
	v_mfma_f32_32x32x16_bf16 v[50:65], v[10:13], v[6:9], 0
	v_or_b32_e32 v10, 64, v154
	v_or_b32_e32 v11, s6, v10
	v_mul_lo_u32 v11, v11, s48
	v_lshrrev_b32_e32 v192, 3, v10
	v_add_u32_e32 v191, 0, v11
	v_xor_b32_e32 v10, v192, v140
	v_lshl_add_u32 v10, v10, 4, v191
	s_waitcnt lgkmcnt(2)
	v_mfma_f32_32x32x16_bf16 v[98:113], v[14:17], v[2:5], 0
	ds_read_b128 v[10:13], v10
	v_xor_b32_e32 v153, v192, v152
	v_lshl_add_u32 v153, v153, 4, v191
	v_mfma_f32_32x32x16_bf16 v[34:49], v[14:17], v[6:9], 0
	v_or_b32_e32 v14, 0x60, v154
	v_or_b32_e32 v15, s6, v14
	v_mul_lo_u32 v15, v15, s48
	v_lshrrev_b32_e32 v194, 3, v14
	v_add_u32_e32 v193, 0, v15
	v_xor_b32_e32 v14, v194, v140
	v_lshl_add_u32 v14, v14, 4, v193
	ds_read_b128 v[14:17], v14
	v_xor_b32_e32 v152, v194, v152
	v_lshl_add_u32 v152, v152, 4, v193
	s_waitcnt vmcnt(9) lgkmcnt(3)
	v_mfma_f32_32x32x16_bf16 v[114:129], v[180:183], v[144:147], v[114:129]
	s_waitcnt vmcnt(6)
	v_mfma_f32_32x32x16_bf16 v[50:65], v[180:183], v[160:163], v[50:65]
	ds_read_b128 v[180:183], v153
	s_waitcnt lgkmcnt(3)
	v_mfma_f32_32x32x16_bf16 v[98:113], v[184:187], v[144:147], v[98:113]
	v_mfma_f32_32x32x16_bf16 v[34:49], v[184:187], v[160:163], v[34:49]
	ds_read_b128 v[184:187], v152
	v_add_u32_e32 v152, 4, v140
	v_xor_b32_e32 v153, v190, v152
	v_lshl_add_u32 v153, v153, 4, v189
	s_waitcnt lgkmcnt(3)
	v_mfma_f32_32x32x16_bf16 v[82:97], v[10:13], v[2:5], 0
	s_waitcnt lgkmcnt(2)
	v_mfma_f32_32x32x16_bf16 v[66:81], v[14:17], v[2:5], 0
	s_waitcnt lgkmcnt(1)
	v_mfma_f32_32x32x16_bf16 v[82:97], v[180:183], v[144:147], v[82:97]
	s_waitcnt lgkmcnt(0)
	v_mfma_f32_32x32x16_bf16 v[66:81], v[184:187], v[144:147], v[66:81]
	v_xor_b32_e32 v144, v188, v152
	v_lshl_add_u32 v144, v144, 4, v155
	ds_read_b128 v[144:147], v144
	v_mfma_f32_32x32x16_bf16 v[18:33], v[10:13], v[6:9], 0
	v_mfma_f32_32x32x16_bf16 v[2:17], v[14:17], v[6:9], 0
	v_mfma_f32_32x32x16_bf16 v[18:33], v[180:183], v[160:163], v[18:33]
	v_mfma_f32_32x32x16_bf16 v[2:17], v[184:187], v[160:163], v[2:17]
	ds_read_b128 v[160:163], v153
	s_waitcnt lgkmcnt(1)
	v_mfma_f32_32x32x16_bf16 v[114:129], v[144:147], v[148:151], v[114:129]
	s_waitcnt vmcnt(5)
	v_mfma_f32_32x32x16_bf16 v[50:65], v[144:147], v[164:167], v[50:65]
	v_xor_b32_e32 v144, v192, v152
	v_lshl_add_u32 v144, v144, 4, v191
	ds_read_b128 v[144:147], v144
	v_xor_b32_e32 v152, v194, v152
	v_lshl_add_u32 v152, v152, 4, v193
	s_waitcnt lgkmcnt(1)
	v_mfma_f32_32x32x16_bf16 v[98:113], v[160:163], v[148:151], v[98:113]
	v_mfma_f32_32x32x16_bf16 v[34:49], v[160:163], v[164:167], v[34:49]
	ds_read_b128 v[160:163], v152
	v_add_u32_e32 v152, 6, v140
	s_waitcnt lgkmcnt(1)
	v_mfma_f32_32x32x16_bf16 v[82:97], v[144:147], v[148:151], v[82:97]
	v_mfma_f32_32x32x16_bf16 v[18:33], v[144:147], v[164:167], v[18:33]
	v_xor_b32_e32 v144, v188, v152
	v_lshl_add_u32 v144, v144, 4, v155
	ds_read_b128 v[144:147], v144
	s_waitcnt lgkmcnt(1)
	v_mfma_f32_32x32x16_bf16 v[66:81], v[160:163], v[148:151], v[66:81]
	v_xor_b32_e32 v148, v190, v152
	v_lshl_add_u32 v148, v148, 4, v189
	ds_read_b128 v[148:151], v148
	s_waitcnt lgkmcnt(1)
	v_mfma_f32_32x32x16_bf16 v[114:129], v[144:147], v[156:159], v[114:129]
	s_waitcnt vmcnt(4)
	v_mfma_f32_32x32x16_bf16 v[50:65], v[144:147], v[168:171], v[50:65]
	v_xor_b32_e32 v144, v192, v152
	v_lshl_add_u32 v144, v144, 4, v191
	ds_read_b128 v[144:147], v144
	s_waitcnt lgkmcnt(1)
	v_mfma_f32_32x32x16_bf16 v[98:113], v[148:151], v[156:159], v[98:113]
	v_mfma_f32_32x32x16_bf16 v[34:49], v[148:151], v[168:171], v[34:49]
	v_xor_b32_e32 v148, v194, v152
	v_lshl_add_u32 v148, v148, 4, v193
	v_add_u32_e32 v152, 8, v140
	ds_read_b128 v[148:151], v148
	s_waitcnt lgkmcnt(1)
	v_mfma_f32_32x32x16_bf16 v[82:97], v[144:147], v[156:159], v[82:97]
	v_mfma_f32_32x32x16_bf16 v[18:33], v[144:147], v[168:171], v[18:33]
	v_xor_b32_e32 v144, v188, v152
	v_lshl_add_u32 v144, v144, 4, v155
	ds_read_b128 v[144:147], v144
	v_mfma_f32_32x32x16_bf16 v[2:17], v[160:163], v[164:167], v[2:17]
	s_waitcnt lgkmcnt(1)
	v_mfma_f32_32x32x16_bf16 v[66:81], v[148:151], v[156:159], v[66:81]
	v_or_b32_e32 v157, s21, v154
	v_or_b32_e32 v156, s50, v157
	v_mfma_f32_32x32x16_bf16 v[2:17], v[148:151], v[168:171], v[2:17]
	v_xor_b32_e32 v148, v190, v152
	v_lshl_add_u32 v148, v148, 4, v189
	ds_read_b128 v[148:151], v148
	s_waitcnt vmcnt(3) lgkmcnt(1)
	v_mfma_f32_32x32x16_bf16 v[50:65], v[144:147], v[172:175], v[50:65]
	v_xor_b32_e32 v144, v192, v152
	v_lshl_add_u32 v144, v144, 4, v191
	ds_read_b128 v[144:147], v144
	s_waitcnt lgkmcnt(1)
	v_mfma_f32_32x32x16_bf16 v[34:49], v[148:151], v[172:175], v[34:49]
	v_xor_b32_e32 v148, v194, v152
	v_lshl_add_u32 v148, v148, 4, v193
	v_add_u32_e32 v152, 10, v140
	ds_read_b128 v[148:151], v148
	s_waitcnt lgkmcnt(1)
	v_mfma_f32_32x32x16_bf16 v[18:33], v[144:147], v[172:175], v[18:33]
	v_xor_b32_e32 v144, v188, v152
	v_lshl_add_u32 v144, v144, 4, v155
	ds_read_b128 v[144:147], v144
	s_waitcnt lgkmcnt(1)
	v_mfma_f32_32x32x16_bf16 v[2:17], v[148:151], v[172:175], v[2:17]
	v_xor_b32_e32 v148, v190, v152
	v_lshl_add_u32 v148, v148, 4, v189
	ds_read_b128 v[148:151], v148
	s_waitcnt vmcnt(2) lgkmcnt(1)
	v_mfma_f32_32x32x16_bf16 v[50:65], v[144:147], v[176:179], v[50:65]
	v_xor_b32_e32 v144, v192, v152
	v_lshl_add_u32 v144, v144, 4, v191
	ds_read_b128 v[144:147], v144
	s_waitcnt lgkmcnt(1)
; __device__ __forceinline__ void gmlp_unit(const GmlpP& P, int b, int ch, LAS unsigned char* lds, int wave, int lane_in) {
;     ...
;         const int t = 32 * (nt == 0 ? tt0 : tt1) + r32;
;         const float bsv = P.bs[gI * 128 + t];
;         const bf16_t* up = P.U + (tok0 + t) * GW + gI * 128 + 4 * h;
;         float ss = 0.f;
;         u32x2 uraw[4][4];
; #pragma unroll
;         for (int mt = 0; mt < 4; ++mt)
; #pragma unroll
;             for (int e4 = 0; e4 < 4; ++e4) uraw[mt][e4] = *(const u32x2*)(up + 32 * mt + 8 * e4);
; #pragma unroll
;         for (int mt = 0; mt < 4; ++mt)
; #pragma unroll
;             for (int e4 = 0; e4 < 4; ++e4) {
;                 const u32x2 raw = uraw[mt][e4];
;                 const float u0 = __builtin_bit_cast(float, raw.x << 16), u1 = __builtin_bit_cast(float, raw.x & 0xffff0000u);
;                 const float u2 = __builtin_bit_cast(float, raw.y << 16), u3 = __builtin_bit_cast(float, raw.y & 0xffff0000u);
;                 float m0 = u0 * (acc[mt][nt][4 * e4] + bsv), m1 = u1 * (acc[mt][nt][4 * e4 + 1] + bsv), m2 = u2 * (acc[mt][nt][4 * e4 + 2] + bsv), m3 = u3 * (acc[mt][nt][4 * e4 + 3] + bsv);
;                 acc[mt][nt][4 * e4] = m0; acc[mt][nt][4 * e4 + 1] = m1; acc[mt][nt][4 * e4 + 2] = m2; acc[mt][nt][4 * e4 + 3] = m3;
;                 ss += (m0 * m0 + m1 * m1) + (m2 * m2 + m3 * m3);
	v_mfma_f32_32x32x16_bf16 v[34:49], v[148:151], v[176:179], v[34:49]
	v_xor_b32_e32 v148, v194, v152
	v_lshl_add_u32 v148, v148, 4, v193
	v_add_u32_e32 v152, 12, v140
	ds_read_b128 v[148:151], v148
	s_waitcnt lgkmcnt(1)
	v_mfma_f32_32x32x16_bf16 v[18:33], v[144:147], v[176:179], v[18:33]
	v_xor_b32_e32 v144, v188, v152
	v_lshl_add_u32 v144, v144, 4, v155
	ds_read_b128 v[144:147], v144
	s_waitcnt lgkmcnt(1)
	v_mfma_f32_32x32x16_bf16 v[2:17], v[148:151], v[176:179], v[2:17]
	v_xor_b32_e32 v148, v190, v152
	v_lshl_add_u32 v148, v148, 4, v189
	ds_read_b128 v[148:151], v148
	s_waitcnt vmcnt(1) lgkmcnt(1)
	v_mfma_f32_32x32x16_bf16 v[50:65], v[144:147], v[134:137], v[50:65]
	v_xor_b32_e32 v144, v192, v152
	v_lshl_add_u32 v144, v144, 4, v191
	ds_read_b128 v[144:147], v144
	s_waitcnt lgkmcnt(1)
	v_mfma_f32_32x32x16_bf16 v[34:49], v[148:151], v[134:137], v[34:49]
	v_xor_b32_e32 v148, v194, v152
	v_lshl_add_u32 v148, v148, 4, v193
	ds_read_b128 v[150:153], v148
	v_or_b32_e32 v148, s6, v157
	v_ashrrev_i32_e32 v149, 31, v148
	v_lshl_add_u64 v[178:179], v[148:149], 2, s[40:41]
	s_waitcnt lgkmcnt(1)
	v_mfma_f32_32x32x16_bf16 v[18:33], v[144:147], v[134:137], v[18:33]
	v_add_u32_e32 v144, 14, v140
	v_xor_b32_e32 v145, v188, v144
	v_lshl_add_u32 v145, v145, 4, v155
	v_xor_b32_e32 v146, v190, v144
	v_lshl_add_u32 v146, v146, 4, v189
	ds_read_b128 v[158:161], v145
	ds_read_b128 v[162:165], v146
	v_xor_b32_e32 v145, v192, v144
	v_xor_b32_e32 v144, v194, v144
	v_lshl_add_u32 v145, v145, 4, v191
	v_lshl_add_u32 v144, v144, 4, v193
	ds_read_b128 v[166:169], v145
	ds_read_b128 v[170:173], v144
	v_lshlrev_b32_e32 v144, 2, v140
	v_ashrrev_i32_e32 v145, 31, v144
	v_lshl_add_u64 v[146:147], v[144:145], 1, s[14:15]
	v_lshlrev_b32_e32 v140, 10, v156
	v_lshl_add_u64 v[174:175], v[146:147], 0, v[140:141]
	global_load_dword v140, v[178:179], off
	v_bfe_u32 v234, v0, 5, 1
	v_lshlrev_b32_e32 v234, 3, v234
	v_mov_b32_e32 v235, 0
	v_lshl_add_u64 v[234:235], v[174:175], 0, v[234:235]
	global_load_dwordx4 v[202:205], v[234:235], off
	global_load_dwordx4 v[206:209], v[234:235], off offset:32
	global_load_dwordx4 v[210:213], v[234:235], off offset:64
	global_load_dwordx4 v[214:217], v[234:235], off offset:96
	global_load_dwordx4 v[218:221], v[234:235], off offset:128
	global_load_dwordx4 v[222:225], v[234:235], off offset:160
	global_load_dwordx4 v[226:229], v[234:235], off offset:192
	global_load_dwordx4 v[230:233], v[234:235], off offset:224
	s_waitcnt vmcnt(9) lgkmcnt(3)
	v_mfma_f32_32x32x16_bf16 v[50:65], v[158:161], v[130:133], v[50:65]
	s_waitcnt vmcnt(8)
	v_add_f32_e64 v114, v114, v140
	v_add_f32_e64 v115, v115, v140
	s_waitcnt lgkmcnt(2)
	v_mfma_f32_32x32x16_bf16 v[34:49], v[162:165], v[130:133], v[34:49]
	v_add_f32_e64 v116, v116, v140
	v_add_f32_e64 v117, v117, v140
	v_add_f32_e64 v118, v118, v140
	v_add_f32_e64 v119, v119, v140
	v_pk_add_f32 v[120:121], v[120:121], v[140:141] op_sel_hi:[1,0]
	v_pk_add_f32 v[122:123], v[122:123], v[140:141] op_sel_hi:[1,0]
	v_pk_add_f32 v[124:125], v[124:125], v[140:141] op_sel_hi:[1,0]
	v_pk_add_f32 v[126:127], v[126:127], v[140:141] op_sel_hi:[1,0]
	v_mfma_f32_32x32x16_bf16 v[2:17], v[150:153], v[134:137], v[2:17]
	v_add_f32_e64 v128, v128, v140
	v_add_f32_e64 v129, v129, v140
	v_add_f32_e64 v98, v98, v140
	v_add_f32_e64 v99, v99, v140
	v_add_f32_e64 v100, v100, v140
	v_add_f32_e64 v101, v101, v140
	v_pk_add_f32 v[102:103], v[102:103], v[140:141] op_sel_hi:[1,0]
	v_pk_add_f32 v[104:105], v[104:105], v[140:141] op_sel_hi:[1,0]
	v_pk_add_f32 v[106:107], v[106:107], v[140:141] op_sel_hi:[1,0]
	v_pk_add_f32 v[108:109], v[108:109], v[140:141] op_sel_hi:[1,0]
	s_waitcnt lgkmcnt(1)
	v_mfma_f32_32x32x16_bf16 v[18:33], v[166:169], v[130:133], v[18:33]
	v_add_f32_e64 v110, v110, v140
	v_add_f32_e64 v111, v111, v140
	v_add_f32_e64 v112, v112, v140
	v_add_f32_e64 v113, v113, v140
	v_add_f32_e64 v82, v82, v140
	v_add_f32_e64 v83, v83, v140
	v_pk_add_f32 v[84:85], v[84:85], v[140:141] op_sel_hi:[1,0]
	v_pk_add_f32 v[86:87], v[86:87], v[140:141] op_sel_hi:[1,0]
	v_pk_add_f32 v[88:89], v[88:89], v[140:141] op_sel_hi:[1,0]
	v_pk_add_f32 v[90:91], v[90:91], v[140:141] op_sel_hi:[1,0]
	s_waitcnt lgkmcnt(0)
	v_mfma_f32_32x32x16_bf16 v[2:17], v[170:173], v[130:133], v[2:17]
	s_waitcnt vmcnt(0)
	v_permlane32_swap_b32_e32 v202, v204
	v_permlane32_swap_b32_e32 v203, v205
	v_permlane32_swap_b32_e32 v206, v208
	v_permlane32_swap_b32_e32 v207, v209
	v_permlane32_swap_b32_e32 v210, v212
	v_permlane32_swap_b32_e32 v211, v213
	v_permlane32_swap_b32_e32 v214, v216
	v_permlane32_swap_b32_e32 v215, v217
	v_permlane32_swap_b32_e32 v218, v220
	v_permlane32_swap_b32_e32 v219, v221
	v_permlane32_swap_b32_e32 v222, v224
	v_permlane32_swap_b32_e32 v223, v225
	v_permlane32_swap_b32_e32 v226, v228
	v_permlane32_swap_b32_e32 v227, v229
	v_permlane32_swap_b32_e32 v230, v232
	v_permlane32_swap_b32_e32 v231, v233
	v_mov_b32_e32 v176, v202
	v_mov_b32_e32 v177, v203
	v_mov_b32_e32 v178, v204
	v_mov_b32_e32 v179, v205
	v_mov_b32_e32 v158, v206
	v_mov_b32_e32 v159, v207
	v_mov_b32_e32 v160, v208
	v_mov_b32_e32 v161, v209
	v_mov_b32_e32 v162, v210
	v_mov_b32_e32 v163, v211
	v_mov_b32_e32 v164, v212
	v_mov_b32_e32 v165, v213
	v_mov_b32_e32 v166, v214
	v_mov_b32_e32 v167, v215
	v_mov_b32_e32 v168, v216
	v_mov_b32_e32 v169, v217
	v_mov_b32_e32 v170, v218
	v_mov_b32_e32 v171, v219
	v_mov_b32_e32 v172, v220
	v_mov_b32_e32 v173, v221
	v_mov_b32_e32 v180, v222
	v_mov_b32_e32 v181, v223
	v_mov_b32_e32 v152, v224
	v_mov_b32_e32 v153, v225
	v_mov_b32_e32 v150, v226
	v_mov_b32_e32 v151, v227
	v_mov_b32_e32 v136, v228
	v_mov_b32_e32 v137, v229
	v_mov_b32_e32 v134, v230
	v_mov_b32_e32 v135, v231
	v_mov_b32_e32 v132, v232
	v_mov_b32_e32 v133, v233
	v_lshlrev_b32_e32 v130, 16, v176
	v_and_b32_e32 v131, 0xffff0000, v176
	v_pk_mul_f32 v[114:115], v[114:115], v[130:131]
	v_lshlrev_b32_e32 v130, 16, v177
	v_and_b32_e32 v131, 0xffff0000, v177
	v_pk_mul_f32 v[116:117], v[116:117], v[130:131]
	v_mul_f32_e32 v130, v115, v115
	v_mul_f32_e32 v174, v117, v117
	v_pk_fma_f32 v[130:131], v[114:115], v[114:115], v[130:131] op_sel_hi:[1,1,0]
	v_pk_fma_f32 v[174:175], v[116:117], v[116:117], v[174:175] op_sel_hi:[1,1,0]
	v_pk_add_f32 v[92:93], v[92:93], v[140:141] op_sel_hi:[1,0]
	v_pk_add_f32 v[174:175], v[130:131], v[174:175]
	s_waitcnt vmcnt(14)
; __device__ __forceinline__ void gmlp_unit(const GmlpP& P, int b, int ch, LAS unsigned char* lds, int wave, int lane_in) {
;     ...
; #pragma unroll
;         for (int mt = 0; mt < 4; ++mt)
; #pragma unroll
;             for (int e4 = 0; e4 < 4; ++e4) {
;                 const u32x2 raw = uraw[mt][e4];
;                 const float u0 = __builtin_bit_cast(float, raw.x << 16), u1 = __builtin_bit_cast(float, raw.x & 0xffff0000u);
;                 const float u2 = __builtin_bit_cast(float, raw.y << 16), u3 = __builtin_bit_cast(float, raw.y & 0xffff0000u);
;                 float m0 = u0 * (acc[mt][nt][4 * e4] + bsv), m1 = u1 * (acc[mt][nt][4 * e4 + 1] + bsv), m2 = u2 * (acc[mt][nt][4 * e4 + 2] + bsv), m3 = u3 * (acc[mt][nt][4 * e4 + 3] + bsv);
;                 acc[mt][nt][4 * e4] = m0; acc[mt][nt][4 * e4 + 1] = m1; acc[mt][nt][4 * e4 + 2] = m2; acc[mt][nt][4 * e4 + 3] = m3;
;                 ss += (m0 * m0 + m1 * m1) + (m2 * m2 + m3 * m3);
;             }
	v_lshlrev_b32_e32 v130, 16, v178
	v_and_b32_e32 v131, 0xffff0000, v178
	v_pk_mul_f32 v[118:119], v[118:119], v[130:131]
	v_lshlrev_b32_e32 v130, 16, v179
	v_and_b32_e32 v131, 0xffff0000, v179
	v_pk_mul_f32 v[130:131], v[120:121], v[130:131]
	v_mul_f32_e32 v120, v119, v119
	v_mul_f32_e32 v176, v131, v131
	v_pk_fma_f32 v[120:121], v[118:119], v[118:119], v[120:121] op_sel_hi:[1,1,0]
	v_pk_fma_f32 v[176:177], v[130:131], v[130:131], v[176:177] op_sel_hi:[1,1,0]
	v_pk_add_f32 v[94:95], v[94:95], v[140:141] op_sel_hi:[1,0]
	v_pk_add_f32 v[120:121], v[120:121], v[176:177]
	v_pk_add_f32 v[96:97], v[96:97], v[140:141] op_sel_hi:[1,0]
	v_pk_add_f32 v[174:175], v[174:175], v[120:121]
	s_waitcnt vmcnt(13)
	v_lshlrev_b32_e32 v120, 16, v158
	v_and_b32_e32 v121, 0xffff0000, v158
	v_pk_mul_f32 v[122:123], v[122:123], v[120:121]
	v_lshlrev_b32_e32 v120, 16, v159
	v_and_b32_e32 v121, 0xffff0000, v159
	v_pk_mul_f32 v[120:121], v[124:125], v[120:121]
	v_mul_f32_e32 v124, v123, v123
	v_mul_f32_e32 v158, v121, v121
	v_pk_fma_f32 v[124:125], v[122:123], v[122:123], v[124:125] op_sel_hi:[1,1,0]
	v_pk_fma_f32 v[158:159], v[120:121], v[120:121], v[158:159] op_sel_hi:[1,1,0]
	v_pk_add_f32 v[66:67], v[66:67], v[140:141] op_sel_hi:[1,0]
	v_pk_add_f32 v[124:125], v[124:125], v[158:159]
	v_pk_add_f32 v[68:69], v[68:69], v[140:141] op_sel_hi:[1,0]
	v_pk_add_f32 v[158:159], v[174:175], v[124:125]
	s_waitcnt vmcnt(12)
	v_lshlrev_b32_e32 v124, 16, v160
	v_and_b32_e32 v125, 0xffff0000, v160
	v_pk_mul_f32 v[124:125], v[126:127], v[124:125]
	v_lshlrev_b32_e32 v126, 16, v161
	v_and_b32_e32 v127, 0xffff0000, v161
	v_pk_mul_f32 v[126:127], v[128:129], v[126:127]
	v_mul_f32_e32 v128, v125, v125
	v_mul_f32_e32 v160, v127, v127
	v_pk_fma_f32 v[128:129], v[124:125], v[124:125], v[128:129] op_sel_hi:[1,1,0]
	v_pk_fma_f32 v[160:161], v[126:127], v[126:127], v[160:161] op_sel_hi:[1,1,0]
	v_pk_add_f32 v[70:71], v[70:71], v[140:141] op_sel_hi:[1,0]
	v_pk_add_f32 v[128:129], v[128:129], v[160:161]
	v_pk_add_f32 v[72:73], v[72:73], v[140:141] op_sel_hi:[1,0]
	v_pk_add_f32 v[128:129], v[158:159], v[128:129]
	v_pk_add_f32 v[74:75], v[74:75], v[140:141] op_sel_hi:[1,0]
	s_waitcnt vmcnt(11)
	v_lshlrev_b32_e32 v158, 16, v162
	v_and_b32_e32 v159, 0xffff0000, v162
	v_pk_mul_f32 v[98:99], v[98:99], v[158:159]
	v_lshlrev_b32_e32 v158, 16, v163
	v_and_b32_e32 v159, 0xffff0000, v163
	v_pk_mul_f32 v[100:101], v[100:101], v[158:159]
	v_mul_f32_e32 v158, v99, v99
	v_mul_f32_e32 v160, v101, v101
	v_pk_fma_f32 v[158:159], v[98:99], v[98:99], v[158:159] op_sel_hi:[1,1,0]
	v_pk_fma_f32 v[160:161], v[100:101], v[100:101], v[160:161] op_sel_hi:[1,1,0]
	v_pk_add_f32 v[76:77], v[76:77], v[140:141] op_sel_hi:[1,0]
	v_pk_add_f32 v[158:159], v[158:159], v[160:161]
	v_pk_add_f32 v[78:79], v[78:79], v[140:141] op_sel_hi:[1,0]
	v_pk_add_f32 v[158:159], v[128:129], v[158:159]
	s_waitcnt vmcnt(10)
	v_lshlrev_b32_e32 v128, 16, v164
	v_and_b32_e32 v129, 0xffff0000, v164
	v_pk_mul_f32 v[102:103], v[102:103], v[128:129]
	v_lshlrev_b32_e32 v128, 16, v165
	v_and_b32_e32 v129, 0xffff0000, v165
	v_pk_mul_f32 v[128:129], v[104:105], v[128:129]
	v_mul_f32_e32 v104, v103, v103
	v_mul_f32_e32 v160, v129, v129
	v_pk_fma_f32 v[104:105], v[102:103], v[102:103], v[104:105] op_sel_hi:[1,1,0]
	v_pk_fma_f32 v[160:161], v[128:129], v[128:129], v[160:161] op_sel_hi:[1,1,0]
	v_pk_add_f32 v[80:81], v[80:81], v[140:141] op_sel_hi:[1,0]
	v_pk_add_f32 v[104:105], v[104:105], v[160:161]
	s_nop 0
	v_pk_add_f32 v[158:159], v[158:159], v[104:105]
	s_waitcnt vmcnt(9)
	v_lshlrev_b32_e32 v104, 16, v166
	v_and_b32_e32 v105, 0xffff0000, v166
	v_pk_mul_f32 v[106:107], v[106:107], v[104:105]
	v_lshlrev_b32_e32 v104, 16, v167
	v_and_b32_e32 v105, 0xffff0000, v167
	v_pk_mul_f32 v[104:105], v[108:109], v[104:105]
	v_mul_f32_e32 v108, v107, v107
	v_mul_f32_e32 v160, v105, v105
	v_pk_fma_f32 v[108:109], v[106:107], v[106:107], v[108:109] op_sel_hi:[1,1,0]
	v_pk_fma_f32 v[160:161], v[104:105], v[104:105], v[160:161] op_sel_hi:[1,1,0]
	s_nop 0
	v_pk_add_f32 v[108:109], v[108:109], v[160:161]
	s_nop 0
	v_pk_add_f32 v[158:159], v[158:159], v[108:109]
	s_waitcnt vmcnt(8)
	v_lshlrev_b32_e32 v108, 16, v168
	v_and_b32_e32 v109, 0xffff0000, v168
	v_pk_mul_f32 v[108:109], v[110:111], v[108:109]
	v_lshlrev_b32_e32 v110, 16, v169
	v_and_b32_e32 v111, 0xffff0000, v169
	v_pk_mul_f32 v[110:111], v[112:113], v[110:111]
	v_mul_f32_e32 v112, v109, v109
	v_mul_f32_e32 v160, v111, v111
	v_pk_fma_f32 v[112:113], v[108:109], v[108:109], v[112:113] op_sel_hi:[1,1,0]
	v_pk_fma_f32 v[160:161], v[110:111], v[110:111], v[160:161] op_sel_hi:[1,1,0]
	s_nop 0
	v_pk_add_f32 v[112:113], v[112:113], v[160:161]
	s_nop 0
	v_pk_add_f32 v[112:113], v[158:159], v[112:113]
	s_waitcnt vmcnt(7)
	v_lshlrev_b32_e32 v158, 16, v170
	v_and_b32_e32 v159, 0xffff0000, v170
	v_pk_mul_f32 v[82:83], v[82:83], v[158:159]
	v_lshlrev_b32_e32 v158, 16, v171
	v_and_b32_e32 v159, 0xffff0000, v171
	v_pk_mul_f32 v[84:85], v[84:85], v[158:159]
	v_mul_f32_e32 v158, v83, v83
	v_mul_f32_e32 v160, v85, v85
	v_pk_fma_f32 v[158:159], v[82:83], v[82:83], v[158:159] op_sel_hi:[1,1,0]
	v_pk_fma_f32 v[160:161], v[84:85], v[84:85], v[160:161] op_sel_hi:[1,1,0]
	s_nop 0
	v_pk_add_f32 v[158:159], v[158:159], v[160:161]
	s_nop 0
	v_pk_add_f32 v[158:159], v[112:113], v[158:159]
	s_waitcnt vmcnt(6)
	v_lshlrev_b32_e32 v112, 16, v172
	v_and_b32_e32 v113, 0xffff0000, v172
	v_pk_mul_f32 v[86:87], v[86:87], v[112:113]
	v_lshlrev_b32_e32 v112, 16, v173
	v_and_b32_e32 v113, 0xffff0000, v173
	v_pk_mul_f32 v[112:113], v[88:89], v[112:113]
	v_mul_f32_e32 v88, v87, v87
	v_mul_f32_e32 v160, v113, v113
	v_pk_fma_f32 v[88:89], v[86:87], v[86:87], v[88:89] op_sel_hi:[1,1,0]
	v_pk_fma_f32 v[160:161], v[112:113], v[112:113], v[160:161] op_sel_hi:[1,1,0]
	s_nop 0
	v_pk_add_f32 v[88:89], v[88:89], v[160:161]
	s_nop 0
	v_pk_add_f32 v[158:159], v[158:159], v[88:89]
	s_waitcnt vmcnt(5)
; __device__ __forceinline__ void gmlp_unit(const GmlpP& P, int b, int ch, LAS unsigned char* lds, int wave, int lane_in) {
;     ...
;         const int t = 32 * (nt == 0 ? tt0 : tt1) + r32;
;         const float bsv = P.bs[gI * 128 + t];
;         const bf16_t* up = P.U + (tok0 + t) * GW + gI * 128 + 4 * h;
;         float ss = 0.f;
;         u32x2 uraw[4][4];
; #pragma unroll
;         for (int mt = 0; mt < 4; ++mt)
; #pragma unroll
;             for (int e4 = 0; e4 < 4; ++e4) uraw[mt][e4] = *(const u32x2*)(up + 32 * mt + 8 * e4);
; #pragma unroll
;         for (int mt = 0; mt < 4; ++mt)
; #pragma unroll
;             for (int e4 = 0; e4 < 4; ++e4) {
;                 const u32x2 raw = uraw[mt][e4];
;                 const float u0 = __builtin_bit_cast(float, raw.x << 16), u1 = __builtin_bit_cast(float, raw.x & 0xffff0000u);
;                 const float u2 = __builtin_bit_cast(float, raw.y << 16), u3 = __builtin_bit_cast(float, raw.y & 0xffff0000u);
;                 float m0 = u0 * (acc[mt][nt][4 * e4] + bsv), m1 = u1 * (acc[mt][nt][4 * e4 + 1] + bsv), m2 = u2 * (acc[mt][nt][4 * e4 + 2] + bsv), m3 = u3 * (acc[mt][nt][4 * e4 + 3] + bsv);
;                 acc[mt][nt][4 * e4] = m0; acc[mt][nt][4 * e4 + 1] = m1; acc[mt][nt][4 * e4 + 2] = m2; acc[mt][nt][4 * e4 + 3] = m3;
;                 ss += (m0 * m0 + m1 * m1) + (m2 * m2 + m3 * m3);
;             }
;         ss = xor32_sum(ss);
;         if (h == 0) ssqg[gI * 128 + t] = ss;
	v_lshlrev_b32_e32 v88, 16, v180
	v_and_b32_e32 v89, 0xffff0000, v180
	v_pk_mul_f32 v[90:91], v[90:91], v[88:89]
	v_lshlrev_b32_e32 v88, 16, v181
	v_and_b32_e32 v89, 0xffff0000, v181
	v_pk_mul_f32 v[88:89], v[92:93], v[88:89]
	v_mul_f32_e32 v92, v91, v91
	v_mul_f32_e32 v160, v89, v89
	v_pk_fma_f32 v[92:93], v[90:91], v[90:91], v[92:93] op_sel_hi:[1,1,0]
	v_pk_fma_f32 v[160:161], v[88:89], v[88:89], v[160:161] op_sel_hi:[1,1,0]
	s_nop 0
	v_pk_add_f32 v[92:93], v[92:93], v[160:161]
	s_nop 0
	v_pk_add_f32 v[158:159], v[158:159], v[92:93]
	s_waitcnt vmcnt(4)
	v_lshlrev_b32_e32 v92, 16, v152
	v_and_b32_e32 v93, 0xffff0000, v152
	v_pk_mul_f32 v[92:93], v[94:95], v[92:93]
	v_lshlrev_b32_e32 v94, 16, v153
	v_and_b32_e32 v95, 0xffff0000, v153
	v_pk_mul_f32 v[94:95], v[96:97], v[94:95]
	v_mul_f32_e32 v96, v93, v93
	v_mul_f32_e32 v152, v95, v95
	v_pk_fma_f32 v[96:97], v[92:93], v[92:93], v[96:97] op_sel_hi:[1,1,0]
	v_pk_fma_f32 v[152:153], v[94:95], v[94:95], v[152:153] op_sel_hi:[1,1,0]
	s_nop 0
	v_pk_add_f32 v[96:97], v[96:97], v[152:153]
	s_waitcnt vmcnt(3)
	v_lshlrev_b32_e32 v152, 16, v150
	v_and_b32_e32 v153, 0xffff0000, v150
	v_lshlrev_b32_e32 v150, 16, v151
	v_and_b32_e32 v151, 0xffff0000, v151
	v_pk_mul_f32 v[66:67], v[66:67], v[152:153]
	v_pk_mul_f32 v[68:69], v[68:69], v[150:151]
	v_mul_f32_e32 v150, v67, v67
	v_mul_f32_e32 v152, v69, v69
	v_pk_fma_f32 v[150:151], v[66:67], v[66:67], v[150:151] op_sel_hi:[1,1,0]
	v_pk_fma_f32 v[152:153], v[68:69], v[68:69], v[152:153] op_sel_hi:[1,1,0]
	v_pk_add_f32 v[96:97], v[158:159], v[96:97]
	v_pk_add_f32 v[150:151], v[150:151], v[152:153]
	s_nop 0
	v_pk_add_f32 v[150:151], v[96:97], v[150:151]
	s_waitcnt vmcnt(2)
	v_lshlrev_b32_e32 v96, 16, v136
	v_and_b32_e32 v97, 0xffff0000, v136
	v_pk_mul_f32 v[70:71], v[70:71], v[96:97]
	v_lshlrev_b32_e32 v96, 16, v137
	v_and_b32_e32 v97, 0xffff0000, v137
	v_pk_mul_f32 v[96:97], v[72:73], v[96:97]
	v_mul_f32_e32 v72, v71, v71
	v_mul_f32_e32 v136, v97, v97
	v_pk_fma_f32 v[72:73], v[70:71], v[70:71], v[72:73] op_sel_hi:[1,1,0]
	v_pk_fma_f32 v[136:137], v[96:97], v[96:97], v[136:137] op_sel_hi:[1,1,0]
	s_nop 0
	v_pk_add_f32 v[72:73], v[72:73], v[136:137]
	s_nop 0
	v_pk_add_f32 v[136:137], v[150:151], v[72:73]
	s_waitcnt vmcnt(1)
	v_lshlrev_b32_e32 v72, 16, v134
	v_and_b32_e32 v73, 0xffff0000, v134
	v_pk_mul_f32 v[74:75], v[74:75], v[72:73]
	v_lshlrev_b32_e32 v72, 16, v135
	v_and_b32_e32 v73, 0xffff0000, v135
	v_pk_mul_f32 v[72:73], v[76:77], v[72:73]
	v_mul_f32_e32 v76, v75, v75
	v_mul_f32_e32 v134, v73, v73
	v_pk_fma_f32 v[76:77], v[74:75], v[74:75], v[76:77] op_sel_hi:[1,1,0]
	v_pk_fma_f32 v[134:135], v[72:73], v[72:73], v[134:135] op_sel_hi:[1,1,0]
	s_nop 0
	v_pk_add_f32 v[76:77], v[76:77], v[134:135]
	s_nop 0
	v_pk_add_f32 v[134:135], v[136:137], v[76:77]
	s_waitcnt vmcnt(0)
	v_lshlrev_b32_e32 v76, 16, v132
	v_and_b32_e32 v77, 0xffff0000, v132
	v_pk_mul_f32 v[76:77], v[78:79], v[76:77]
	v_lshlrev_b32_e32 v78, 16, v133
	v_and_b32_e32 v79, 0xffff0000, v133
	v_pk_mul_f32 v[78:79], v[80:81], v[78:79]
	v_mul_f32_e32 v80, v77, v77
	v_mul_f32_e32 v132, v79, v79
	v_pk_fma_f32 v[80:81], v[76:77], v[76:77], v[80:81] op_sel_hi:[1,1,0]
	v_pk_fma_f32 v[132:133], v[78:79], v[78:79], v[132:133] op_sel_hi:[1,1,0]
	s_nop 0
	v_pk_add_f32 v[80:81], v[80:81], v[132:133]
	s_nop 0
	v_pk_add_f32 v[80:81], v[134:135], v[80:81]
	s_nop 0
	v_mov_b32_e32 v81, v80
	s_nop 1
	v_permlane32_swap_b32_e32 v80, v81
	s_and_saveexec_b64 s[26:27], vcc
	v_add_f32_e32 v80, v80, v81
	v_lshl_add_u32 v81, v148, 2, 0
	v_add_u32_e32 v81, 0x22000, v81
	ds_write_b32 v81, v80
	s_or_b64 exec, exec, s[26:27]
	v_add_u32_e32 v140, s31, v154
	v_lshl_add_u64 v[80:81], v[140:141], 0, s[6:7]
	v_lshl_add_u64 v[80:81], v[80:81], 2, s[40:41]
	global_load_dword v150, v[80:81], off offset:256
	v_or_b32_e32 v158, s23, v154
	v_or_b32_e32 v139, s50, v158
	v_lshlrev_b32_e32 v140, 10, v139
	v_lshl_add_u64 v[152:153], v[146:147], 0, v[140:141]
	v_bfe_u32 v234, v0, 5, 1
	v_lshlrev_b32_e32 v234, 3, v234
	v_mov_b32_e32 v235, 0
	v_lshl_add_u64 v[234:235], v[152:153], 0, v[234:235]
	global_load_dwordx4 v[202:205], v[234:235], off
	global_load_dwordx4 v[206:209], v[234:235], off offset:32
	global_load_dwordx4 v[210:213], v[234:235], off offset:64
	global_load_dwordx4 v[214:217], v[234:235], off offset:96
	global_load_dwordx4 v[218:221], v[234:235], off offset:128
	global_load_dwordx4 v[222:225], v[234:235], off offset:160
	global_load_dwordx4 v[226:229], v[234:235], off offset:192
	global_load_dwordx4 v[230:233], v[234:235], off offset:224
	s_waitcnt vmcnt(0)
	v_permlane32_swap_b32_e32 v202, v204
	v_permlane32_swap_b32_e32 v203, v205
	v_permlane32_swap_b32_e32 v206, v208
	v_permlane32_swap_b32_e32 v207, v209
	v_permlane32_swap_b32_e32 v210, v212
	v_permlane32_swap_b32_e32 v211, v213
	v_permlane32_swap_b32_e32 v214, v216
	v_permlane32_swap_b32_e32 v215, v217
	v_permlane32_swap_b32_e32 v218, v220
	v_permlane32_swap_b32_e32 v219, v221
	v_permlane32_swap_b32_e32 v222, v224
	v_permlane32_swap_b32_e32 v223, v225
	v_permlane32_swap_b32_e32 v226, v228
	v_permlane32_swap_b32_e32 v227, v229
	v_permlane32_swap_b32_e32 v230, v232
	v_permlane32_swap_b32_e32 v231, v233
	v_mov_b32_e32 v160, v202
	v_mov_b32_e32 v161, v203
	v_mov_b32_e32 v162, v204
	v_mov_b32_e32 v163, v205
	v_mov_b32_e32 v164, v206
	v_mov_b32_e32 v165, v207
	v_mov_b32_e32 v166, v208
	v_mov_b32_e32 v167, v209
	v_mov_b32_e32 v168, v210
	v_mov_b32_e32 v169, v211
	v_mov_b32_e32 v170, v212
	v_mov_b32_e32 v171, v213
	v_mov_b32_e32 v172, v214
	v_mov_b32_e32 v173, v215
	v_mov_b32_e32 v174, v216
	v_mov_b32_e32 v175, v217
	v_mov_b32_e32 v154, v218
	v_mov_b32_e32 v155, v219
	v_mov_b32_e32 v146, v220
	v_mov_b32_e32 v147, v221
	v_mov_b32_e32 v134, v222
	v_mov_b32_e32 v135, v223
	v_mov_b32_e32 v80, v224
	v_mov_b32_e32 v81, v225
	v_mov_b32_e32 v132, v226
	v_mov_b32_e32 v133, v227
	v_mov_b32_e32 v136, v228
	v_mov_b32_e32 v137, v229
	v_mov_b32_e32 v148, v230
	v_mov_b32_e32 v149, v231
	v_mov_b32_e32 v152, v232
	v_mov_b32_e32 v153, v233
	s_waitcnt vmcnt(12)
; __device__ __forceinline__ void gmlp_unit(const GmlpP& P, int b, int ch, LAS unsigned char* lds, int wave, int lane_in) {
;     ...
; #pragma unroll
;         for (int mt = 0; mt < 4; ++mt)
; #pragma unroll
;             for (int e4 = 0; e4 < 4; ++e4) {
;                 const u32x2 raw = uraw[mt][e4];
;                 const float u0 = __builtin_bit_cast(float, raw.x << 16), u1 = __builtin_bit_cast(float, raw.x & 0xffff0000u);
;                 const float u2 = __builtin_bit_cast(float, raw.y << 16), u3 = __builtin_bit_cast(float, raw.y & 0xffff0000u);
;                 float m0 = u0 * (acc[mt][nt][4 * e4] + bsv), m1 = u1 * (acc[mt][nt][4 * e4 + 1] + bsv), m2 = u2 * (acc[mt][nt][4 * e4 + 2] + bsv), m3 = u3 * (acc[mt][nt][4 * e4 + 3] + bsv);
;                 acc[mt][nt][4 * e4] = m0; acc[mt][nt][4 * e4 + 1] = m1; acc[mt][nt][4 * e4 + 2] = m2; acc[mt][nt][4 * e4 + 3] = m3;
;                 ss += (m0 * m0 + m1 * m1) + (m2 * m2 + m3 * m3);
;             }
	v_lshlrev_b32_e32 v186, 16, v166
	s_waitcnt vmcnt(11)
	v_lshlrev_b32_e32 v188, 16, v168
	v_and_b32_e32 v189, 0xffff0000, v168
	v_lshlrev_b32_e32 v168, 16, v169
	v_and_b32_e32 v169, 0xffff0000, v169
	v_and_b32_e32 v187, 0xffff0000, v166
	v_lshlrev_b32_e32 v166, 16, v167
	v_pk_add_f32 v[50:51], v[50:51], v[150:151] op_sel_hi:[1,0]
	v_pk_add_f32 v[52:53], v[52:53], v[150:151] op_sel_hi:[1,0]
	v_pk_add_f32 v[54:55], v[54:55], v[150:151] op_sel_hi:[1,0]
	v_pk_add_f32 v[56:57], v[56:57], v[150:151] op_sel_hi:[1,0]
	v_pk_add_f32 v[176:177], v[58:59], v[150:151] op_sel_hi:[1,0]
	v_pk_add_f32 v[178:179], v[60:61], v[150:151] op_sel_hi:[1,0]
	v_pk_add_f32 v[184:185], v[36:37], v[150:151] op_sel_hi:[1,0]
	v_lshlrev_b32_e32 v36, 16, v160
	v_and_b32_e32 v37, 0xffff0000, v160
	v_lshlrev_b32_e32 v58, 16, v161
	v_and_b32_e32 v59, 0xffff0000, v161
	v_lshlrev_b32_e32 v60, 16, v162
	v_and_b32_e32 v61, 0xffff0000, v162
	v_lshlrev_b32_e32 v160, 16, v163
	v_and_b32_e32 v161, 0xffff0000, v163
	v_pk_add_f32 v[180:181], v[62:63], v[150:151] op_sel_hi:[1,0]
	v_pk_add_f32 v[182:183], v[64:65], v[150:151] op_sel_hi:[1,0]
	v_lshlrev_b32_e32 v162, 16, v164
	v_and_b32_e32 v163, 0xffff0000, v164
	v_lshlrev_b32_e32 v164, 16, v165
	v_and_b32_e32 v165, 0xffff0000, v165
	v_pk_mul_f32 v[64:65], v[50:51], v[36:37]
	v_pk_mul_f32 v[62:63], v[52:53], v[58:59]
	v_pk_mul_f32 v[60:61], v[54:55], v[60:61]
	v_pk_mul_f32 v[58:59], v[56:57], v[160:161]
	v_pk_add_f32 v[34:35], v[34:35], v[150:151] op_sel_hi:[1,0]
	v_pk_mul_f32 v[56:57], v[176:177], v[162:163]
	v_pk_mul_f32 v[54:55], v[178:179], v[164:165]
	v_mul_f32_e32 v140, v65, v65
	v_mul_f32_e32 v160, v63, v63
	v_mul_f32_e32 v162, v61, v61
	v_mul_f32_e32 v164, v59, v59
	v_pk_mul_f32 v[36:37], v[34:35], v[188:189]
	v_pk_mul_f32 v[34:35], v[184:185], v[168:169]
	v_pk_fma_f32 v[184:185], v[64:65], v[64:65], v[140:141] op_sel_hi:[1,1,0]
	v_pk_fma_f32 v[160:161], v[62:63], v[62:63], v[160:161] op_sel_hi:[1,1,0]
	v_pk_fma_f32 v[162:163], v[60:61], v[60:61], v[162:163] op_sel_hi:[1,1,0]
	v_pk_fma_f32 v[164:165], v[58:59], v[58:59], v[164:165] op_sel_hi:[1,1,0]
	v_and_b32_e32 v167, 0xffff0000, v167
	v_pk_add_f32 v[160:161], v[184:185], v[160:161]
	v_pk_add_f32 v[162:163], v[162:163], v[164:165]
	v_pk_mul_f32 v[52:53], v[180:181], v[186:187]
	v_pk_mul_f32 v[50:51], v[182:183], v[166:167]
	v_mul_f32_e32 v166, v57, v57
	v_mul_f32_e32 v168, v55, v55
	v_pk_add_f32 v[160:161], v[160:161], v[162:163]
	s_waitcnt vmcnt(10)
	v_lshlrev_b32_e32 v162, 16, v170
	v_and_b32_e32 v163, 0xffff0000, v170
	v_pk_add_f32 v[38:39], v[38:39], v[150:151] op_sel_hi:[1,0]
	v_mul_f32_e32 v176, v53, v53
	v_mul_f32_e32 v178, v51, v51
	v_pk_fma_f32 v[166:167], v[56:57], v[56:57], v[166:167] op_sel_hi:[1,1,0]
	v_pk_fma_f32 v[168:169], v[54:55], v[54:55], v[168:169] op_sel_hi:[1,1,0]
	v_pk_mul_f32 v[38:39], v[38:39], v[162:163]
	v_lshlrev_b32_e32 v162, 16, v171
	v_and_b32_e32 v163, 0xffff0000, v171
	v_pk_add_f32 v[40:41], v[40:41], v[150:151] op_sel_hi:[1,0]
	v_mul_f32_e32 v180, v37, v37
	v_mul_f32_e32 v182, v35, v35
	v_pk_fma_f32 v[176:177], v[52:53], v[52:53], v[176:177] op_sel_hi:[1,1,0]
	v_pk_fma_f32 v[178:179], v[50:51], v[50:51], v[178:179] op_sel_hi:[1,1,0]
	v_pk_add_f32 v[164:165], v[166:167], v[168:169]
	v_pk_mul_f32 v[40:41], v[40:41], v[162:163]
	v_mul_f32_e32 v140, v39, v39
	v_pk_fma_f32 v[180:181], v[36:37], v[36:37], v[180:181] op_sel_hi:[1,1,0]
	v_pk_fma_f32 v[182:183], v[34:35], v[34:35], v[182:183] op_sel_hi:[1,1,0]
	v_pk_add_f32 v[166:167], v[176:177], v[178:179]
	v_pk_add_f32 v[160:161], v[160:161], v[164:165]
	v_pk_fma_f32 v[162:163], v[38:39], v[38:39], v[140:141] op_sel_hi:[1,1,0]
	v_mul_f32_e32 v140, v41, v41
	v_pk_add_f32 v[168:169], v[180:181], v[182:183]
	v_pk_add_f32 v[160:161], v[160:161], v[166:167]
	v_pk_fma_f32 v[164:165], v[40:41], v[40:41], v[140:141] op_sel_hi:[1,1,0]
	v_pk_add_f32 v[160:161], v[160:161], v[168:169]
	v_pk_add_f32 v[162:163], v[162:163], v[164:165]
	v_pk_add_f32 v[42:43], v[42:43], v[150:151] op_sel_hi:[1,0]
	v_pk_add_f32 v[160:161], v[160:161], v[162:163]
	s_waitcnt vmcnt(9)
	v_lshlrev_b32_e32 v162, 16, v172
	v_and_b32_e32 v163, 0xffff0000, v172
	v_pk_mul_f32 v[42:43], v[42:43], v[162:163]
	v_lshlrev_b32_e32 v162, 16, v173
	v_and_b32_e32 v163, 0xffff0000, v173
	v_pk_add_f32 v[44:45], v[44:45], v[150:151] op_sel_hi:[1,0]
	v_mul_f32_e32 v140, v43, v43
	v_pk_mul_f32 v[44:45], v[44:45], v[162:163]
	v_pk_fma_f32 v[162:163], v[42:43], v[42:43], v[140:141] op_sel_hi:[1,1,0]
	v_mul_f32_e32 v140, v45, v45
	v_pk_fma_f32 v[164:165], v[44:45], v[44:45], v[140:141] op_sel_hi:[1,1,0]
	v_pk_add_f32 v[46:47], v[46:47], v[150:151] op_sel_hi:[1,0]
	v_pk_add_f32 v[162:163], v[162:163], v[164:165]
	v_pk_add_f32 v[48:49], v[48:49], v[150:151] op_sel_hi:[1,0]
	v_pk_add_f32 v[160:161], v[160:161], v[162:163]
	s_waitcnt vmcnt(8)
	v_lshlrev_b32_e32 v162, 16, v174
	v_and_b32_e32 v163, 0xffff0000, v174
	v_pk_mul_f32 v[46:47], v[46:47], v[162:163]
	v_lshlrev_b32_e32 v162, 16, v175
	v_and_b32_e32 v163, 0xffff0000, v175
	v_pk_mul_f32 v[48:49], v[48:49], v[162:163]
	v_mul_f32_e32 v140, v47, v47
	v_pk_fma_f32 v[162:163], v[46:47], v[46:47], v[140:141] op_sel_hi:[1,1,0]
	v_mul_f32_e32 v140, v49, v49
	v_pk_fma_f32 v[164:165], v[48:49], v[48:49], v[140:141] op_sel_hi:[1,1,0]
	v_pk_add_f32 v[18:19], v[18:19], v[150:151] op_sel_hi:[1,0]
	v_pk_add_f32 v[162:163], v[162:163], v[164:165]
	v_pk_add_f32 v[20:21], v[20:21], v[150:151] op_sel_hi:[1,0]
	v_pk_add_f32 v[160:161], v[160:161], v[162:163]
	s_waitcnt vmcnt(7)
; __device__ __forceinline__ void gmlp_unit(const GmlpP& P, int b, int ch, LAS unsigned char* lds, int wave, int lane_in) {
;     ...
; #pragma unroll
;         for (int mt = 0; mt < 4; ++mt)
; #pragma unroll
;             for (int e4 = 0; e4 < 4; ++e4) {
;                 const u32x2 raw = uraw[mt][e4];
;                 const float u0 = __builtin_bit_cast(float, raw.x << 16), u1 = __builtin_bit_cast(float, raw.x & 0xffff0000u);
;                 const float u2 = __builtin_bit_cast(float, raw.y << 16), u3 = __builtin_bit_cast(float, raw.y & 0xffff0000u);
;                 float m0 = u0 * (acc[mt][nt][4 * e4] + bsv), m1 = u1 * (acc[mt][nt][4 * e4 + 1] + bsv), m2 = u2 * (acc[mt][nt][4 * e4 + 2] + bsv), m3 = u3 * (acc[mt][nt][4 * e4 + 3] + bsv);
;                 acc[mt][nt][4 * e4] = m0; acc[mt][nt][4 * e4 + 1] = m1; acc[mt][nt][4 * e4 + 2] = m2; acc[mt][nt][4 * e4 + 3] = m3;
;                 ss += (m0 * m0 + m1 * m1) + (m2 * m2 + m3 * m3);
;             }
;         ss = xor32_sum(ss);
;         if (h == 0) ssqg[gI * 128 + t] = ss;
	v_lshlrev_b32_e32 v162, 16, v154
	v_and_b32_e32 v163, 0xffff0000, v154
	v_pk_mul_f32 v[18:19], v[18:19], v[162:163]
	v_lshlrev_b32_e32 v154, 16, v155
	v_and_b32_e32 v155, 0xffff0000, v155
	v_pk_mul_f32 v[20:21], v[20:21], v[154:155]
	v_mul_f32_e32 v140, v19, v19
	v_pk_fma_f32 v[154:155], v[18:19], v[18:19], v[140:141] op_sel_hi:[1,1,0]
	v_mul_f32_e32 v140, v21, v21
	v_pk_fma_f32 v[162:163], v[20:21], v[20:21], v[140:141] op_sel_hi:[1,1,0]
	v_pk_add_f32 v[22:23], v[22:23], v[150:151] op_sel_hi:[1,0]
	v_pk_add_f32 v[154:155], v[154:155], v[162:163]
	v_pk_add_f32 v[24:25], v[24:25], v[150:151] op_sel_hi:[1,0]
	v_pk_add_f32 v[154:155], v[160:161], v[154:155]
	s_waitcnt vmcnt(6)
	v_lshlrev_b32_e32 v160, 16, v146
	v_and_b32_e32 v161, 0xffff0000, v146
	v_pk_mul_f32 v[22:23], v[22:23], v[160:161]
	v_lshlrev_b32_e32 v146, 16, v147
	v_and_b32_e32 v147, 0xffff0000, v147
	v_pk_mul_f32 v[24:25], v[24:25], v[146:147]
	v_mul_f32_e32 v140, v23, v23
	v_pk_fma_f32 v[146:147], v[22:23], v[22:23], v[140:141] op_sel_hi:[1,1,0]
	v_mul_f32_e32 v140, v25, v25
	v_pk_fma_f32 v[160:161], v[24:25], v[24:25], v[140:141] op_sel_hi:[1,1,0]
	v_pk_add_f32 v[26:27], v[26:27], v[150:151] op_sel_hi:[1,0]
	v_pk_add_f32 v[146:147], v[146:147], v[160:161]
	v_pk_add_f32 v[28:29], v[28:29], v[150:151] op_sel_hi:[1,0]
	v_pk_add_f32 v[146:147], v[154:155], v[146:147]
	s_waitcnt vmcnt(5)
	v_lshlrev_b32_e32 v154, 16, v134
	v_and_b32_e32 v155, 0xffff0000, v134
	v_lshlrev_b32_e32 v134, 16, v135
	v_and_b32_e32 v135, 0xffff0000, v135
	v_pk_mul_f32 v[26:27], v[26:27], v[154:155]
	v_pk_mul_f32 v[28:29], v[28:29], v[134:135]
	v_mul_f32_e32 v134, v27, v27
	v_mul_f32_e32 v140, v29, v29
	v_pk_fma_f32 v[134:135], v[26:27], v[26:27], v[134:135] op_sel_hi:[1,1,0]
	v_pk_fma_f32 v[154:155], v[28:29], v[28:29], v[140:141] op_sel_hi:[1,1,0]
	v_pk_add_f32 v[30:31], v[30:31], v[150:151] op_sel_hi:[1,0]
	v_pk_add_f32 v[134:135], v[134:135], v[154:155]
	v_pk_add_f32 v[32:33], v[32:33], v[150:151] op_sel_hi:[1,0]
	v_pk_add_f32 v[134:135], v[146:147], v[134:135]
	s_waitcnt vmcnt(4)
	v_lshlrev_b32_e32 v146, 16, v80
	v_and_b32_e32 v147, 0xffff0000, v80
	v_lshlrev_b32_e32 v80, 16, v81
	v_and_b32_e32 v81, 0xffff0000, v81
	v_pk_mul_f32 v[30:31], v[30:31], v[146:147]
	v_pk_mul_f32 v[32:33], v[32:33], v[80:81]
	v_mul_f32_e32 v80, v31, v31
	v_mul_f32_e32 v140, v33, v33
	v_pk_fma_f32 v[80:81], v[30:31], v[30:31], v[80:81] op_sel_hi:[1,1,0]
	v_pk_fma_f32 v[146:147], v[32:33], v[32:33], v[140:141] op_sel_hi:[1,1,0]
	v_pk_add_f32 v[2:3], v[2:3], v[150:151] op_sel_hi:[1,0]
	v_pk_add_f32 v[80:81], v[80:81], v[146:147]
	v_pk_add_f32 v[4:5], v[4:5], v[150:151] op_sel_hi:[1,0]
	v_pk_add_f32 v[134:135], v[134:135], v[80:81]
	s_waitcnt vmcnt(3)
	v_lshlrev_b32_e32 v80, 16, v132
	v_and_b32_e32 v81, 0xffff0000, v132
	v_pk_mul_f32 v[80:81], v[2:3], v[80:81]
	v_lshlrev_b32_e32 v2, 16, v133
	v_and_b32_e32 v3, 0xffff0000, v133
	v_pk_mul_f32 v[132:133], v[4:5], v[2:3]
	v_mul_f32_e32 v2, v81, v81
	v_mul_f32_e32 v4, v133, v133
	v_pk_fma_f32 v[2:3], v[80:81], v[80:81], v[2:3] op_sel_hi:[1,1,0]
	v_pk_fma_f32 v[4:5], v[132:133], v[132:133], v[4:5] op_sel_hi:[1,1,0]
	v_pk_add_f32 v[6:7], v[6:7], v[150:151] op_sel_hi:[1,0]
	v_pk_add_f32 v[2:3], v[2:3], v[4:5]
	s_waitcnt vmcnt(2)
	v_lshlrev_b32_e32 v4, 16, v136
	v_and_b32_e32 v5, 0xffff0000, v136
	v_pk_add_f32 v[2:3], v[134:135], v[2:3]
	v_pk_mul_f32 v[134:135], v[6:7], v[4:5]
	v_lshlrev_b32_e32 v4, 16, v137
	v_and_b32_e32 v5, 0xffff0000, v137
	v_pk_add_f32 v[6:7], v[8:9], v[150:151] op_sel_hi:[1,0]
	s_nop 0
	v_pk_mul_f32 v[136:137], v[6:7], v[4:5]
	v_mul_f32_e32 v4, v135, v135
	v_mul_f32_e32 v6, v137, v137
	v_pk_fma_f32 v[4:5], v[134:135], v[134:135], v[4:5] op_sel_hi:[1,1,0]
	v_pk_fma_f32 v[6:7], v[136:137], v[136:137], v[6:7] op_sel_hi:[1,1,0]
	s_nop 0
	v_pk_add_f32 v[4:5], v[4:5], v[6:7]
	v_pk_add_f32 v[6:7], v[10:11], v[150:151] op_sel_hi:[1,0]
	v_pk_add_f32 v[2:3], v[2:3], v[4:5]
	s_waitcnt vmcnt(1)
	v_lshlrev_b32_e32 v4, 16, v148
	v_and_b32_e32 v5, 0xffff0000, v148
	v_pk_mul_f32 v[146:147], v[6:7], v[4:5]
	v_lshlrev_b32_e32 v4, 16, v149
	v_and_b32_e32 v5, 0xffff0000, v149
	v_pk_add_f32 v[6:7], v[12:13], v[150:151] op_sel_hi:[1,0]
	s_nop 0
	v_pk_mul_f32 v[148:149], v[6:7], v[4:5]
	v_mul_f32_e32 v4, v147, v147
	v_mul_f32_e32 v6, v149, v149
	v_pk_fma_f32 v[4:5], v[146:147], v[146:147], v[4:5] op_sel_hi:[1,1,0]
	v_pk_fma_f32 v[6:7], v[148:149], v[148:149], v[6:7] op_sel_hi:[1,1,0]
	s_nop 0
	v_pk_add_f32 v[4:5], v[4:5], v[6:7]
	v_pk_add_f32 v[6:7], v[14:15], v[150:151] op_sel_hi:[1,0]
	v_pk_add_f32 v[2:3], v[2:3], v[4:5]
	s_waitcnt vmcnt(0)
	v_lshlrev_b32_e32 v4, 16, v152
	v_and_b32_e32 v5, 0xffff0000, v152
	v_pk_mul_f32 v[14:15], v[6:7], v[4:5]
	v_lshlrev_b32_e32 v4, 16, v153
	v_and_b32_e32 v5, 0xffff0000, v153
	v_pk_add_f32 v[6:7], v[16:17], v[150:151] op_sel_hi:[1,0]
	s_nop 0
	v_pk_mul_f32 v[16:17], v[6:7], v[4:5]
	v_mul_f32_e32 v4, v15, v15
	v_mul_f32_e32 v6, v17, v17
	v_pk_fma_f32 v[4:5], v[14:15], v[14:15], v[4:5] op_sel_hi:[1,1,0]
	v_pk_fma_f32 v[6:7], v[16:17], v[16:17], v[6:7] op_sel_hi:[1,1,0]
	s_nop 0
	v_pk_add_f32 v[4:5], v[4:5], v[6:7]
	s_nop 0
	v_pk_add_f32 v[2:3], v[2:3], v[4:5]
	s_nop 0
	v_mov_b32_e32 v3, v2
	s_nop 1
	v_permlane32_swap_b32_e32 v2, v3
	s_and_saveexec_b64 s[26:27], vcc
	s_cbranch_execz .LBB0_536
	v_or_b32_e32 v4, s6, v158
	v_add_f32_e32 v2, v2, v3
	v_lshl_add_u32 v3, v4, 2, 0
	v_add_u32_e32 v3, 0x22000, v3
	ds_write_b32 v3, v2
	s_branch .LBB0_536
